# GEMM K loops: counter/pointer updates and exit test moved in front of the loop-back barrier (back-edge rotation)
# baseline (speedup 1.0000x reference)
.Lgp_215:
.LBB0_215:
	ds_read_b128 v[144:147], v151
	ds_read_b128 v[154:157], v151 offset:1024
	ds_read_b128 v[158:161], v151 offset:2048
	ds_read_b128 v[162:165], v151 offset:3072
	ds_read_b128 v[166:169], v152
	ds_read_b128 v[170:173], v152 offset:1024
	ds_read_b128 v[174:177], v152 offset:2048
	ds_read_b128 v[178:181], v152 offset:3072
	s_add_u32 s58, s54, 0xfffc0080
	s_addc_u32 s59, s55, -1
	s_cmp_eq_u32 s90, 12
	s_cselect_b32 s61, s19, s59
	s_cselect_b32 s60, s86, s58
	s_cselect_b32 s59, s15, s89
	s_cselect_b32 s58, s87, s88
	v_lshl_add_u64 v[198:199], s[54:55], 0, v[136:137]
	s_add_i32 m0, s4, 0xc000
	ds_read_b128 v[182:185], v153
	ds_read_b128 v[186:189], v153 offset:1024
	ds_read_b128 v[190:193], v153 offset:2048
	ds_read_b128 v[194:197], v153 offset:3072
	ds_read_b128 v[202:205], v153 offset:4096
	ds_read_b128 v[206:209], v153 offset:5120
	ds_read_b128 v[210:213], v153 offset:6144
	ds_read_b128 v[214:217], v153 offset:7168
	global_load_lds_dwordx4 v[198:199], off
	v_lshl_add_u64 v[198:199], s[54:55], 0, v[138:139]
	s_add_i32 m0, s4, 0xe000
	s_nop 0
	global_load_lds_dwordx4 v[198:199], off
	s_waitcnt vmcnt(8)
	s_waitcnt lgkmcnt(0)
	s_barrier
	s_waitcnt lgkmcnt(0)
	v_mfma_f32_16x16x32_bf16 v[124:127], v[144:147], v[182:185], v[124:127]
	v_mfma_f32_16x16x32_bf16 v[120:123], v[158:161], v[182:185], v[120:123]
	v_mfma_f32_16x16x32_bf16 v[116:119], v[144:147], v[190:193], v[116:119]
	v_mfma_f32_16x16x32_bf16 v[108:111], v[158:161], v[190:193], v[108:111]
	v_mfma_f32_16x16x32_bf16 v[100:103], v[144:147], v[202:205], v[100:103]
	v_mfma_f32_16x16x32_bf16 v[92:95], v[158:161], v[202:205], v[92:95]
	v_mfma_f32_16x16x32_bf16 v[84:87], v[144:147], v[210:213], v[84:87]
	v_mfma_f32_16x16x32_bf16 v[76:79], v[158:161], v[210:213], v[76:79]
	v_mfma_f32_16x16x32_bf16 v[124:127], v[154:157], v[186:189], v[124:127]
	v_mfma_f32_16x16x32_bf16 v[120:123], v[162:165], v[186:189], v[120:123]
	v_mfma_f32_16x16x32_bf16 v[116:119], v[154:157], v[194:197], v[116:119]
	v_mfma_f32_16x16x32_bf16 v[108:111], v[162:165], v[194:197], v[108:111]
	v_mfma_f32_16x16x32_bf16 v[100:103], v[154:157], v[206:209], v[100:103]
	v_mfma_f32_16x16x32_bf16 v[92:95], v[162:165], v[206:209], v[92:95]
	v_mfma_f32_16x16x32_bf16 v[84:87], v[154:157], v[214:217], v[84:87]
	v_mfma_f32_16x16x32_bf16 v[76:79], v[162:165], v[214:217], v[76:79]
	v_mfma_f32_16x16x32_bf16 v[112:115], v[166:169], v[182:185], v[112:115]
	v_mfma_f32_16x16x32_bf16 v[104:107], v[174:177], v[182:185], v[104:107]
	v_mfma_f32_16x16x32_bf16 v[96:99], v[166:169], v[190:193], v[96:99]
	v_mfma_f32_16x16x32_bf16 v[88:91], v[174:177], v[190:193], v[88:91]
	v_mfma_f32_16x16x32_bf16 v[80:83], v[166:169], v[202:205], v[80:83]
	v_mfma_f32_16x16x32_bf16 v[72:75], v[174:177], v[202:205], v[72:75]
	v_mfma_f32_16x16x32_bf16 v[68:71], v[166:169], v[210:213], v[68:71]
	v_mfma_f32_16x16x32_bf16 v[64:67], v[174:177], v[210:213], v[64:67]
	v_mfma_f32_16x16x32_bf16 v[112:115], v[170:173], v[186:189], v[112:115]
	v_mfma_f32_16x16x32_bf16 v[104:107], v[178:181], v[186:189], v[104:107]
	v_mfma_f32_16x16x32_bf16 v[96:99], v[170:173], v[194:197], v[96:99]
	v_mfma_f32_16x16x32_bf16 v[88:91], v[178:181], v[194:197], v[88:91]
	v_mfma_f32_16x16x32_bf16 v[80:83], v[170:173], v[206:209], v[80:83]
	v_mfma_f32_16x16x32_bf16 v[72:75], v[178:181], v[206:209], v[72:75]
	v_mfma_f32_16x16x32_bf16 v[68:71], v[170:173], v[214:217], v[68:71]
	v_mfma_f32_16x16x32_bf16 v[64:67], v[178:181], v[214:217], v[64:67]
	s_barrier
	s_add_i32 s91, s17, s66
	v_lshl_add_u64 v[198:199], s[58:59], 0, v[132:133]
	s_mov_b32 m0, s91
	ds_read_b128 v[182:185], v153 offset:16384
	ds_read_b128 v[186:189], v153 offset:17408
	ds_read_b128 v[190:193], v153 offset:18432
	ds_read_b128 v[194:197], v153 offset:19456
	ds_read_b128 v[202:205], v153 offset:20480
	ds_read_b128 v[206:209], v153 offset:21504
	ds_read_b128 v[210:213], v153 offset:22528
	ds_read_b128 v[214:217], v153 offset:23552
	global_load_lds_dwordx4 v[198:199], off
	s_add_i32 m0, s91, 0x2000
	s_add_u32 s92, s58, 0x40000
	v_lshl_add_u64 v[218:219], s[58:59], 0, v[128:129]
	s_addc_u32 s93, s59, 0
	s_add_i32 s91, s80, s66
	global_load_lds_dwordx4 v[218:219], off
	v_lshl_add_u64 v[220:221], s[92:93], 0, v[132:133]
	s_mov_b32 m0, s91
	v_lshl_add_u64 v[222:223], s[60:61], 0, v[130:131]
	global_load_lds_dwordx4 v[220:221], off
	v_lshl_add_u64 v[220:221], s[92:93], 0, v[128:129]
	s_add_i32 m0, s91, 0x2000
	s_nop 0
	global_load_lds_dwordx4 v[220:221], off
	v_lshl_add_u64 v[220:221], s[60:61], 0, v[134:135]
	s_mov_b32 m0, s4
	s_nop 0
	global_load_lds_dwordx4 v[220:221], off
	s_mov_b32 m0, s67
	s_nop 0
	global_load_lds_dwordx4 v[222:223], off
	s_waitcnt vmcnt(8)
	s_waitcnt lgkmcnt(0)
	s_barrier
	s_waitcnt lgkmcnt(0)
	v_mfma_f32_16x16x32_bf16 v[60:63], v[144:147], v[182:185], v[60:63]
	v_mfma_f32_16x16x32_bf16 v[56:59], v[158:161], v[182:185], v[56:59]
	v_mfma_f32_16x16x32_bf16 v[52:55], v[144:147], v[190:193], v[52:55]
	v_mfma_f32_16x16x32_bf16 v[44:47], v[158:161], v[190:193], v[44:47]
	v_mfma_f32_16x16x32_bf16 v[36:39], v[144:147], v[202:205], v[36:39]
	v_mfma_f32_16x16x32_bf16 v[28:31], v[158:161], v[202:205], v[28:31]
	v_mfma_f32_16x16x32_bf16 v[20:23], v[144:147], v[210:213], v[20:23]
	v_mfma_f32_16x16x32_bf16 v[12:15], v[158:161], v[210:213], v[12:15]
	v_mfma_f32_16x16x32_bf16 v[60:63], v[154:157], v[186:189], v[60:63]
	v_mfma_f32_16x16x32_bf16 v[56:59], v[162:165], v[186:189], v[56:59]
	v_mfma_f32_16x16x32_bf16 v[52:55], v[154:157], v[194:197], v[52:55]
	v_mfma_f32_16x16x32_bf16 v[44:47], v[162:165], v[194:197], v[44:47]
	v_mfma_f32_16x16x32_bf16 v[36:39], v[154:157], v[206:209], v[36:39]
	v_mfma_f32_16x16x32_bf16 v[28:31], v[162:165], v[206:209], v[28:31]
	v_mfma_f32_16x16x32_bf16 v[20:23], v[154:157], v[214:217], v[20:23]
	v_mfma_f32_16x16x32_bf16 v[12:15], v[162:165], v[214:217], v[12:15]
	v_mfma_f32_16x16x32_bf16 v[48:51], v[166:169], v[182:185], v[48:51]
	v_mfma_f32_16x16x32_bf16 v[40:43], v[174:177], v[182:185], v[40:43]
	v_mfma_f32_16x16x32_bf16 v[32:35], v[166:169], v[190:193], v[32:35]
	v_mfma_f32_16x16x32_bf16 v[24:27], v[174:177], v[190:193], v[24:27]
	v_mfma_f32_16x16x32_bf16 v[16:19], v[166:169], v[202:205], v[16:19]
	v_mfma_f32_16x16x32_bf16 v[8:11], v[174:177], v[202:205], v[8:11]
	v_mfma_f32_16x16x32_bf16 v[4:7], v[166:169], v[210:213], v[4:7]
	v_mfma_f32_16x16x32_bf16 v[0:3], v[174:177], v[210:213], v[0:3]
	v_mfma_f32_16x16x32_bf16 v[48:51], v[170:173], v[186:189], v[48:51]
	v_mfma_f32_16x16x32_bf16 v[40:43], v[178:181], v[186:189], v[40:43]
	v_mfma_f32_16x16x32_bf16 v[32:35], v[170:173], v[194:197], v[32:35]
	v_mfma_f32_16x16x32_bf16 v[24:27], v[178:181], v[194:197], v[24:27]
	v_mfma_f32_16x16x32_bf16 v[16:19], v[170:173], v[206:209], v[16:19]
	v_mfma_f32_16x16x32_bf16 v[8:11], v[178:181], v[206:209], v[8:11]
	v_mfma_f32_16x16x32_bf16 v[4:7], v[170:173], v[214:217], v[4:7]
	v_mfma_f32_16x16x32_bf16 v[0:3], v[178:181], v[214:217], v[0:3]
	s_barrier
	s_add_i32 s91, 0, 0x18000
	s_add_i32 s92, 0, 0x1c000
	v_add_u32_e32 v162, s91, v149
	v_add_u32_e32 v178, s92, v149
	ds_read_b128 v[144:147], v162
	ds_read_b128 v[154:157], v162 offset:1024
	ds_read_b128 v[158:161], v162 offset:2048
	ds_read_b128 v[162:165], v162 offset:3072
	ds_read_b128 v[166:169], v178
	ds_read_b128 v[170:173], v178 offset:1024
	ds_read_b128 v[174:177], v178 offset:2048
	ds_read_b128 v[178:181], v178 offset:3072
	s_add_u32 s60, s60, 0x40000
	s_addc_u32 s61, s61, 0
	s_mov_b32 m0, s68
	v_lshl_add_u64 v[224:225], s[60:61], 0, v[134:135]
	ds_read_b128 v[182:185], v153 offset:32768
	ds_read_b128 v[186:189], v153 offset:33792
	ds_read_b128 v[190:193], v153 offset:34816
	ds_read_b128 v[194:197], v153 offset:35840
	ds_read_b128 v[202:205], v153 offset:36864
	ds_read_b128 v[206:209], v153 offset:37888
	ds_read_b128 v[210:213], v153 offset:38912
	ds_read_b128 v[214:217], v153 offset:39936
	global_load_lds_dwordx4 v[224:225], off
	v_lshl_add_u64 v[224:225], s[60:61], 0, v[130:131]
	s_mov_b32 m0, s69
	s_nop 0
	global_load_lds_dwordx4 v[224:225], off
	s_waitcnt vmcnt(8)
	s_waitcnt lgkmcnt(0)
	s_barrier
	s_waitcnt lgkmcnt(0)
	v_mfma_f32_16x16x32_bf16 v[124:127], v[144:147], v[182:185], v[124:127]
	v_mfma_f32_16x16x32_bf16 v[120:123], v[158:161], v[182:185], v[120:123]
	v_mfma_f32_16x16x32_bf16 v[116:119], v[144:147], v[190:193], v[116:119]
	v_mfma_f32_16x16x32_bf16 v[108:111], v[158:161], v[190:193], v[108:111]
	v_mfma_f32_16x16x32_bf16 v[100:103], v[144:147], v[202:205], v[100:103]
	v_mfma_f32_16x16x32_bf16 v[92:95], v[158:161], v[202:205], v[92:95]
	v_mfma_f32_16x16x32_bf16 v[84:87], v[144:147], v[210:213], v[84:87]
	v_mfma_f32_16x16x32_bf16 v[76:79], v[158:161], v[210:213], v[76:79]
	v_mfma_f32_16x16x32_bf16 v[124:127], v[154:157], v[186:189], v[124:127]
	v_mfma_f32_16x16x32_bf16 v[120:123], v[162:165], v[186:189], v[120:123]
	v_mfma_f32_16x16x32_bf16 v[116:119], v[154:157], v[194:197], v[116:119]
	v_mfma_f32_16x16x32_bf16 v[108:111], v[162:165], v[194:197], v[108:111]
	v_mfma_f32_16x16x32_bf16 v[100:103], v[154:157], v[206:209], v[100:103]
	v_mfma_f32_16x16x32_bf16 v[92:95], v[162:165], v[206:209], v[92:95]
	v_mfma_f32_16x16x32_bf16 v[84:87], v[154:157], v[214:217], v[84:87]
	v_mfma_f32_16x16x32_bf16 v[76:79], v[162:165], v[214:217], v[76:79]
	v_mfma_f32_16x16x32_bf16 v[112:115], v[166:169], v[182:185], v[112:115]
	v_mfma_f32_16x16x32_bf16 v[104:107], v[174:177], v[182:185], v[104:107]
	v_mfma_f32_16x16x32_bf16 v[96:99], v[166:169], v[190:193], v[96:99]
	v_mfma_f32_16x16x32_bf16 v[88:91], v[174:177], v[190:193], v[88:91]
	v_mfma_f32_16x16x32_bf16 v[80:83], v[166:169], v[202:205], v[80:83]
	v_mfma_f32_16x16x32_bf16 v[72:75], v[174:177], v[202:205], v[72:75]
	v_mfma_f32_16x16x32_bf16 v[68:71], v[166:169], v[210:213], v[68:71]
	v_mfma_f32_16x16x32_bf16 v[64:67], v[174:177], v[210:213], v[64:67]
	v_mfma_f32_16x16x32_bf16 v[112:115], v[170:173], v[186:189], v[112:115]
	v_mfma_f32_16x16x32_bf16 v[104:107], v[178:181], v[186:189], v[104:107]
	v_mfma_f32_16x16x32_bf16 v[96:99], v[170:173], v[194:197], v[96:99]
	v_mfma_f32_16x16x32_bf16 v[88:91], v[178:181], v[194:197], v[88:91]
	v_mfma_f32_16x16x32_bf16 v[80:83], v[170:173], v[206:209], v[80:83]
	v_mfma_f32_16x16x32_bf16 v[72:75], v[178:181], v[206:209], v[72:75]
	v_mfma_f32_16x16x32_bf16 v[68:71], v[170:173], v[214:217], v[68:71]
	v_mfma_f32_16x16x32_bf16 v[64:67], v[178:181], v[214:217], v[64:67]
	s_barrier
	s_add_i32 s60, s91, s66
	v_lshl_add_u64 v[198:199], v[198:199], 0, s[10:11]
	s_mov_b32 m0, s60
	ds_read_b128 v[182:185], v153 offset:49152
	ds_read_b128 v[186:189], v153 offset:50176
	ds_read_b128 v[190:193], v153 offset:51200
	ds_read_b128 v[194:197], v153 offset:52224
	ds_read_b128 v[202:205], v153 offset:53248
	ds_read_b128 v[206:209], v153 offset:54272
	ds_read_b128 v[210:213], v153 offset:55296
	ds_read_b128 v[214:217], v153 offset:56320
	global_load_lds_dwordx4 v[198:199], off
	s_add_i32 m0, s60, 0x2000
	s_add_u32 s58, s58, 0x40080
	v_lshl_add_u64 v[198:199], v[218:219], 0, s[10:11]
	s_addc_u32 s59, s59, 0
	s_add_i32 s60, s92, s66
	global_load_lds_dwordx4 v[198:199], off
	v_lshl_add_u64 v[198:199], s[58:59], 0, v[132:133]
	s_mov_b32 m0, s60
	s_nop 0
	global_load_lds_dwordx4 v[198:199], off
	v_lshl_add_u64 v[198:199], s[58:59], 0, v[128:129]
	s_add_i32 m0, s60, 0x2000
	s_nop 0
	global_load_lds_dwordx4 v[198:199], off
	v_lshl_add_u64 v[198:199], v[220:221], 0, s[10:11]
	s_mov_b32 m0, s72
	s_nop 0
	global_load_lds_dwordx4 v[198:199], off
	v_lshl_add_u64 v[198:199], v[222:223], 0, s[10:11]
	s_mov_b32 m0, s73
	s_nop 0
	global_load_lds_dwordx4 v[198:199], off
	s_waitcnt vmcnt(8)
	s_waitcnt lgkmcnt(0)
	s_barrier
	s_waitcnt lgkmcnt(0)
	v_mfma_f32_16x16x32_bf16 v[60:63], v[144:147], v[182:185], v[60:63]
	v_mfma_f32_16x16x32_bf16 v[56:59], v[158:161], v[182:185], v[56:59]
	v_mfma_f32_16x16x32_bf16 v[52:55], v[144:147], v[190:193], v[52:55]
	v_mfma_f32_16x16x32_bf16 v[44:47], v[158:161], v[190:193], v[44:47]
	v_mfma_f32_16x16x32_bf16 v[36:39], v[144:147], v[202:205], v[36:39]
	v_mfma_f32_16x16x32_bf16 v[28:31], v[158:161], v[202:205], v[28:31]
	v_mfma_f32_16x16x32_bf16 v[20:23], v[144:147], v[210:213], v[20:23]
	v_mfma_f32_16x16x32_bf16 v[12:15], v[158:161], v[210:213], v[12:15]
	v_mfma_f32_16x16x32_bf16 v[60:63], v[154:157], v[186:189], v[60:63]
	v_mfma_f32_16x16x32_bf16 v[56:59], v[162:165], v[186:189], v[56:59]
	v_mfma_f32_16x16x32_bf16 v[52:55], v[154:157], v[194:197], v[52:55]
	v_mfma_f32_16x16x32_bf16 v[44:47], v[162:165], v[194:197], v[44:47]
	v_mfma_f32_16x16x32_bf16 v[36:39], v[154:157], v[206:209], v[36:39]
	v_mfma_f32_16x16x32_bf16 v[28:31], v[162:165], v[206:209], v[28:31]
	v_mfma_f32_16x16x32_bf16 v[20:23], v[154:157], v[214:217], v[20:23]
	v_mfma_f32_16x16x32_bf16 v[12:15], v[162:165], v[214:217], v[12:15]
	v_mfma_f32_16x16x32_bf16 v[48:51], v[166:169], v[182:185], v[48:51]
	v_mfma_f32_16x16x32_bf16 v[40:43], v[174:177], v[182:185], v[40:43]
	v_mfma_f32_16x16x32_bf16 v[32:35], v[166:169], v[190:193], v[32:35]
	v_mfma_f32_16x16x32_bf16 v[24:27], v[174:177], v[190:193], v[24:27]
	v_mfma_f32_16x16x32_bf16 v[16:19], v[166:169], v[202:205], v[16:19]
	v_mfma_f32_16x16x32_bf16 v[8:11], v[174:177], v[202:205], v[8:11]
	v_mfma_f32_16x16x32_bf16 v[4:7], v[166:169], v[210:213], v[4:7]
	v_mfma_f32_16x16x32_bf16 v[0:3], v[174:177], v[210:213], v[0:3]
	v_mfma_f32_16x16x32_bf16 v[48:51], v[170:173], v[186:189], v[48:51]
	v_mfma_f32_16x16x32_bf16 v[40:43], v[178:181], v[186:189], v[40:43]
	v_mfma_f32_16x16x32_bf16 v[32:35], v[170:173], v[194:197], v[32:35]
	v_mfma_f32_16x16x32_bf16 v[24:27], v[178:181], v[194:197], v[24:27]
	v_mfma_f32_16x16x32_bf16 v[16:19], v[170:173], v[206:209], v[16:19]
	v_mfma_f32_16x16x32_bf16 v[8:11], v[178:181], v[206:209], v[8:11]
	v_mfma_f32_16x16x32_bf16 v[4:7], v[170:173], v[214:217], v[4:7]
	v_mfma_f32_16x16x32_bf16 v[0:3], v[178:181], v[214:217], v[0:3]
	s_add_i32 s90, s90, 2
	s_add_u32 s54, s54, 0x100
	s_addc_u32 s55, s55, 0
	s_add_u32 s88, s88, 0x100
	s_addc_u32 s89, s89, 0
	s_cmp_gt_u32 s90, 13
	s_barrier
	s_cbranch_scc0 .LBB0_215
	s_setprio 0
	s_and_b64 vcc, exec, s[12:13]
	s_cbranch_vccz .LBB0_218
	s_barrier

.Lgp_384:
.LBB0_384:
	ds_read_b128 v[152:155], v149
	ds_read_b128 v[156:159], v149 offset:1024
	ds_read_b128 v[160:163], v149 offset:2048
	ds_read_b128 v[164:167], v149 offset:3072
	ds_read_b128 v[168:171], v150
	ds_read_b128 v[172:175], v150 offset:1024
	ds_read_b128 v[176:179], v150 offset:2048
	ds_read_b128 v[180:183], v150 offset:3072
	s_add_u32 s60, s58, 0xfffc0080
	s_addc_u32 s61, s59, -1
	s_cmp_eq_u32 s92, 12
	s_cselect_b32 s63, s17, s61
	s_cselect_b32 s62, s45, s60
	s_cselect_b32 s61, s35, s91
	s_cselect_b32 s60, s89, s90
	v_lshl_add_u64 v[144:145], s[58:59], 0, v[136:137]
	s_add_i32 m0, s74, 0xc000
	ds_read_b128 v[184:187], v151
	ds_read_b128 v[188:191], v151 offset:1024
	ds_read_b128 v[192:195], v151 offset:2048
	ds_read_b128 v[196:199], v151 offset:3072
	ds_read_b128 v[202:205], v151 offset:4096
	ds_read_b128 v[206:209], v151 offset:5120
	ds_read_b128 v[210:213], v151 offset:6144
	ds_read_b128 v[214:217], v151 offset:7168
	global_load_lds_dwordx4 v[144:145], off
	v_lshl_add_u64 v[144:145], s[58:59], 0, v[138:139]
	s_add_i32 m0, s74, 0xe000
	s_nop 0
	global_load_lds_dwordx4 v[144:145], off
	s_waitcnt vmcnt(8)
	s_waitcnt lgkmcnt(0)
	s_barrier
	s_waitcnt lgkmcnt(0)
	v_mfma_f32_16x16x32_bf16 v[124:127], v[152:155], v[184:187], v[124:127]
	v_mfma_f32_16x16x32_bf16 v[120:123], v[160:163], v[184:187], v[120:123]
	v_mfma_f32_16x16x32_bf16 v[116:119], v[152:155], v[192:195], v[116:119]
	v_mfma_f32_16x16x32_bf16 v[108:111], v[160:163], v[192:195], v[108:111]
	v_mfma_f32_16x16x32_bf16 v[100:103], v[152:155], v[202:205], v[100:103]
	v_mfma_f32_16x16x32_bf16 v[92:95], v[160:163], v[202:205], v[92:95]
	v_mfma_f32_16x16x32_bf16 v[84:87], v[152:155], v[210:213], v[84:87]
	v_mfma_f32_16x16x32_bf16 v[76:79], v[160:163], v[210:213], v[76:79]
	v_mfma_f32_16x16x32_bf16 v[124:127], v[156:159], v[188:191], v[124:127]
	v_mfma_f32_16x16x32_bf16 v[120:123], v[164:167], v[188:191], v[120:123]
	v_mfma_f32_16x16x32_bf16 v[116:119], v[156:159], v[196:199], v[116:119]
	v_mfma_f32_16x16x32_bf16 v[108:111], v[164:167], v[196:199], v[108:111]
	v_mfma_f32_16x16x32_bf16 v[100:103], v[156:159], v[206:209], v[100:103]
	v_mfma_f32_16x16x32_bf16 v[92:95], v[164:167], v[206:209], v[92:95]
	v_mfma_f32_16x16x32_bf16 v[84:87], v[156:159], v[214:217], v[84:87]
	v_mfma_f32_16x16x32_bf16 v[76:79], v[164:167], v[214:217], v[76:79]
	v_mfma_f32_16x16x32_bf16 v[112:115], v[168:171], v[184:187], v[112:115]
	v_mfma_f32_16x16x32_bf16 v[104:107], v[176:179], v[184:187], v[104:107]
	v_mfma_f32_16x16x32_bf16 v[96:99], v[168:171], v[192:195], v[96:99]
	v_mfma_f32_16x16x32_bf16 v[88:91], v[176:179], v[192:195], v[88:91]
	v_mfma_f32_16x16x32_bf16 v[80:83], v[168:171], v[202:205], v[80:83]
	v_mfma_f32_16x16x32_bf16 v[72:75], v[176:179], v[202:205], v[72:75]
	v_mfma_f32_16x16x32_bf16 v[68:71], v[168:171], v[210:213], v[68:71]
	v_mfma_f32_16x16x32_bf16 v[64:67], v[176:179], v[210:213], v[64:67]
	v_mfma_f32_16x16x32_bf16 v[112:115], v[172:175], v[188:191], v[112:115]
	v_mfma_f32_16x16x32_bf16 v[104:107], v[180:183], v[188:191], v[104:107]
	v_mfma_f32_16x16x32_bf16 v[96:99], v[172:175], v[196:199], v[96:99]
	v_mfma_f32_16x16x32_bf16 v[88:91], v[180:183], v[196:199], v[88:91]
	v_mfma_f32_16x16x32_bf16 v[80:83], v[172:175], v[206:209], v[80:83]
	v_mfma_f32_16x16x32_bf16 v[72:75], v[180:183], v[206:209], v[72:75]
	v_mfma_f32_16x16x32_bf16 v[68:71], v[172:175], v[214:217], v[68:71]
	v_mfma_f32_16x16x32_bf16 v[64:67], v[180:183], v[214:217], v[64:67]
	s_barrier
	s_add_i32 s93, s83, s73
	v_lshl_add_u64 v[144:145], s[60:61], 0, v[132:133]
	s_mov_b32 m0, s93
	ds_read_b128 v[184:187], v151 offset:16384
	ds_read_b128 v[188:191], v151 offset:17408
	ds_read_b128 v[192:195], v151 offset:18432
	ds_read_b128 v[196:199], v151 offset:19456
	ds_read_b128 v[202:205], v151 offset:20480
	ds_read_b128 v[206:209], v151 offset:21504
	ds_read_b128 v[210:213], v151 offset:22528
	ds_read_b128 v[214:217], v151 offset:23552
	global_load_lds_dwordx4 v[144:145], off
	s_add_i32 m0, s93, 0x2000
	s_add_u32 s94, s60, 0x40000
	v_lshl_add_u64 v[218:219], s[60:61], 0, v[128:129]
	s_addc_u32 s95, s61, 0
	s_add_i32 s93, s84, s73
	global_load_lds_dwordx4 v[218:219], off
	v_lshl_add_u64 v[220:221], s[94:95], 0, v[132:133]
	s_mov_b32 m0, s93
	v_lshl_add_u64 v[222:223], s[62:63], 0, v[130:131]
	global_load_lds_dwordx4 v[220:221], off
	v_lshl_add_u64 v[220:221], s[94:95], 0, v[128:129]
	s_add_i32 m0, s93, 0x2000
	s_nop 0
	global_load_lds_dwordx4 v[220:221], off
	v_lshl_add_u64 v[220:221], s[62:63], 0, v[134:135]
	s_mov_b32 m0, s74
	s_nop 0
	global_load_lds_dwordx4 v[220:221], off
	s_mov_b32 m0, s75
	s_nop 0
	global_load_lds_dwordx4 v[222:223], off
	s_waitcnt vmcnt(8)
	s_waitcnt lgkmcnt(0)
	s_barrier
	s_waitcnt lgkmcnt(0)
	v_mfma_f32_16x16x32_bf16 v[60:63], v[152:155], v[184:187], v[60:63]
	v_mfma_f32_16x16x32_bf16 v[56:59], v[160:163], v[184:187], v[56:59]
	v_mfma_f32_16x16x32_bf16 v[52:55], v[152:155], v[192:195], v[52:55]
	v_mfma_f32_16x16x32_bf16 v[44:47], v[160:163], v[192:195], v[44:47]
	v_mfma_f32_16x16x32_bf16 v[36:39], v[152:155], v[202:205], v[36:39]
	v_mfma_f32_16x16x32_bf16 v[28:31], v[160:163], v[202:205], v[28:31]
	v_mfma_f32_16x16x32_bf16 v[20:23], v[152:155], v[210:213], v[20:23]
	v_mfma_f32_16x16x32_bf16 v[12:15], v[160:163], v[210:213], v[12:15]
	v_mfma_f32_16x16x32_bf16 v[60:63], v[156:159], v[188:191], v[60:63]
	v_mfma_f32_16x16x32_bf16 v[56:59], v[164:167], v[188:191], v[56:59]
	v_mfma_f32_16x16x32_bf16 v[52:55], v[156:159], v[196:199], v[52:55]
	v_mfma_f32_16x16x32_bf16 v[44:47], v[164:167], v[196:199], v[44:47]
	v_mfma_f32_16x16x32_bf16 v[36:39], v[156:159], v[206:209], v[36:39]
	v_mfma_f32_16x16x32_bf16 v[28:31], v[164:167], v[206:209], v[28:31]
	v_mfma_f32_16x16x32_bf16 v[20:23], v[156:159], v[214:217], v[20:23]
	v_mfma_f32_16x16x32_bf16 v[12:15], v[164:167], v[214:217], v[12:15]
	v_mfma_f32_16x16x32_bf16 v[48:51], v[168:171], v[184:187], v[48:51]
	v_mfma_f32_16x16x32_bf16 v[40:43], v[176:179], v[184:187], v[40:43]
	v_mfma_f32_16x16x32_bf16 v[32:35], v[168:171], v[192:195], v[32:35]
	v_mfma_f32_16x16x32_bf16 v[24:27], v[176:179], v[192:195], v[24:27]
	v_mfma_f32_16x16x32_bf16 v[16:19], v[168:171], v[202:205], v[16:19]
	v_mfma_f32_16x16x32_bf16 v[8:11], v[176:179], v[202:205], v[8:11]
	v_mfma_f32_16x16x32_bf16 v[4:7], v[168:171], v[210:213], v[4:7]
	v_mfma_f32_16x16x32_bf16 v[0:3], v[176:179], v[210:213], v[0:3]
	v_mfma_f32_16x16x32_bf16 v[48:51], v[172:175], v[188:191], v[48:51]
	v_mfma_f32_16x16x32_bf16 v[40:43], v[180:183], v[188:191], v[40:43]
	v_mfma_f32_16x16x32_bf16 v[32:35], v[172:175], v[196:199], v[32:35]
	v_mfma_f32_16x16x32_bf16 v[24:27], v[180:183], v[196:199], v[24:27]
	v_mfma_f32_16x16x32_bf16 v[16:19], v[172:175], v[206:209], v[16:19]
	v_mfma_f32_16x16x32_bf16 v[8:11], v[180:183], v[206:209], v[8:11]
	v_mfma_f32_16x16x32_bf16 v[4:7], v[172:175], v[214:217], v[4:7]
	v_mfma_f32_16x16x32_bf16 v[0:3], v[180:183], v[214:217], v[0:3]
	s_barrier
	s_add_i32 s93, 0, 0x18000
	s_add_i32 s94, 0, 0x1c000
	v_add_u32_e32 v164, s93, v147
	v_add_u32_e32 v180, s94, v147
	ds_read_b128 v[152:155], v164
	ds_read_b128 v[156:159], v164 offset:1024
	ds_read_b128 v[160:163], v164 offset:2048
	ds_read_b128 v[164:167], v164 offset:3072
	ds_read_b128 v[168:171], v180
	ds_read_b128 v[172:175], v180 offset:1024
	ds_read_b128 v[176:179], v180 offset:2048
	ds_read_b128 v[180:183], v180 offset:3072
	s_add_u32 s62, s62, 0x40000
	s_addc_u32 s63, s63, 0
	s_mov_b32 m0, s76
	v_lshl_add_u64 v[224:225], s[62:63], 0, v[134:135]
	ds_read_b128 v[184:187], v151 offset:32768
	ds_read_b128 v[188:191], v151 offset:33792
	ds_read_b128 v[192:195], v151 offset:34816
	ds_read_b128 v[196:199], v151 offset:35840
	ds_read_b128 v[202:205], v151 offset:36864
	ds_read_b128 v[206:209], v151 offset:37888
	ds_read_b128 v[210:213], v151 offset:38912
	ds_read_b128 v[214:217], v151 offset:39936
	global_load_lds_dwordx4 v[224:225], off
	v_lshl_add_u64 v[224:225], s[62:63], 0, v[130:131]
	s_mov_b32 m0, s77
	s_nop 0
	global_load_lds_dwordx4 v[224:225], off
	s_waitcnt vmcnt(8)
	s_waitcnt lgkmcnt(0)
	s_barrier
	s_waitcnt lgkmcnt(0)
	v_mfma_f32_16x16x32_bf16 v[124:127], v[152:155], v[184:187], v[124:127]
	v_mfma_f32_16x16x32_bf16 v[120:123], v[160:163], v[184:187], v[120:123]
	v_mfma_f32_16x16x32_bf16 v[116:119], v[152:155], v[192:195], v[116:119]
	v_mfma_f32_16x16x32_bf16 v[108:111], v[160:163], v[192:195], v[108:111]
	v_mfma_f32_16x16x32_bf16 v[100:103], v[152:155], v[202:205], v[100:103]
	v_mfma_f32_16x16x32_bf16 v[92:95], v[160:163], v[202:205], v[92:95]
	v_mfma_f32_16x16x32_bf16 v[84:87], v[152:155], v[210:213], v[84:87]
	v_mfma_f32_16x16x32_bf16 v[76:79], v[160:163], v[210:213], v[76:79]
	v_mfma_f32_16x16x32_bf16 v[124:127], v[156:159], v[188:191], v[124:127]
	v_mfma_f32_16x16x32_bf16 v[120:123], v[164:167], v[188:191], v[120:123]
	v_mfma_f32_16x16x32_bf16 v[116:119], v[156:159], v[196:199], v[116:119]
	v_mfma_f32_16x16x32_bf16 v[108:111], v[164:167], v[196:199], v[108:111]
	v_mfma_f32_16x16x32_bf16 v[100:103], v[156:159], v[206:209], v[100:103]
	v_mfma_f32_16x16x32_bf16 v[92:95], v[164:167], v[206:209], v[92:95]
	v_mfma_f32_16x16x32_bf16 v[84:87], v[156:159], v[214:217], v[84:87]
	v_mfma_f32_16x16x32_bf16 v[76:79], v[164:167], v[214:217], v[76:79]
	v_mfma_f32_16x16x32_bf16 v[112:115], v[168:171], v[184:187], v[112:115]
	v_mfma_f32_16x16x32_bf16 v[104:107], v[176:179], v[184:187], v[104:107]
	v_mfma_f32_16x16x32_bf16 v[96:99], v[168:171], v[192:195], v[96:99]
	v_mfma_f32_16x16x32_bf16 v[88:91], v[176:179], v[192:195], v[88:91]
	v_mfma_f32_16x16x32_bf16 v[80:83], v[168:171], v[202:205], v[80:83]
	v_mfma_f32_16x16x32_bf16 v[72:75], v[176:179], v[202:205], v[72:75]
	v_mfma_f32_16x16x32_bf16 v[68:71], v[168:171], v[210:213], v[68:71]
	v_mfma_f32_16x16x32_bf16 v[64:67], v[176:179], v[210:213], v[64:67]
	v_mfma_f32_16x16x32_bf16 v[112:115], v[172:175], v[188:191], v[112:115]
	v_mfma_f32_16x16x32_bf16 v[104:107], v[180:183], v[188:191], v[104:107]
	v_mfma_f32_16x16x32_bf16 v[96:99], v[172:175], v[196:199], v[96:99]
	v_mfma_f32_16x16x32_bf16 v[88:91], v[180:183], v[196:199], v[88:91]
	v_mfma_f32_16x16x32_bf16 v[80:83], v[172:175], v[206:209], v[80:83]
	v_mfma_f32_16x16x32_bf16 v[72:75], v[180:183], v[206:209], v[72:75]
	v_mfma_f32_16x16x32_bf16 v[68:71], v[172:175], v[214:217], v[68:71]
	v_mfma_f32_16x16x32_bf16 v[64:67], v[180:183], v[214:217], v[64:67]
	s_barrier
	s_add_i32 s62, s93, s73
	v_lshl_add_u64 v[144:145], v[144:145], 0, s[10:11]
	s_mov_b32 m0, s62
	ds_read_b128 v[184:187], v151 offset:49152
	ds_read_b128 v[188:191], v151 offset:50176
	ds_read_b128 v[192:195], v151 offset:51200
	ds_read_b128 v[196:199], v151 offset:52224
	ds_read_b128 v[202:205], v151 offset:53248
	ds_read_b128 v[206:209], v151 offset:54272
	ds_read_b128 v[210:213], v151 offset:55296
	ds_read_b128 v[214:217], v151 offset:56320
	global_load_lds_dwordx4 v[144:145], off
	s_add_i32 m0, s62, 0x2000
	s_add_u32 s60, s60, 0x40080
	v_lshl_add_u64 v[144:145], v[218:219], 0, s[10:11]
	s_addc_u32 s61, s61, 0
	s_add_i32 s62, s94, s73
	global_load_lds_dwordx4 v[144:145], off
	v_lshl_add_u64 v[144:145], s[60:61], 0, v[132:133]
	s_mov_b32 m0, s62
	s_nop 0
	global_load_lds_dwordx4 v[144:145], off
	v_lshl_add_u64 v[144:145], s[60:61], 0, v[128:129]
	s_add_i32 m0, s62, 0x2000
	s_nop 0
	global_load_lds_dwordx4 v[144:145], off
	v_lshl_add_u64 v[144:145], v[220:221], 0, s[10:11]
	s_mov_b32 m0, s79
	s_nop 0
	global_load_lds_dwordx4 v[144:145], off
	v_lshl_add_u64 v[144:145], v[222:223], 0, s[10:11]
	s_mov_b32 m0, s80
	s_nop 0
	global_load_lds_dwordx4 v[144:145], off
	s_waitcnt vmcnt(8)
	s_waitcnt lgkmcnt(0)
	s_barrier
	s_waitcnt lgkmcnt(0)
	v_mfma_f32_16x16x32_bf16 v[60:63], v[152:155], v[184:187], v[60:63]
	v_mfma_f32_16x16x32_bf16 v[56:59], v[160:163], v[184:187], v[56:59]
	v_mfma_f32_16x16x32_bf16 v[52:55], v[152:155], v[192:195], v[52:55]
	v_mfma_f32_16x16x32_bf16 v[44:47], v[160:163], v[192:195], v[44:47]
	v_mfma_f32_16x16x32_bf16 v[36:39], v[152:155], v[202:205], v[36:39]
	v_mfma_f32_16x16x32_bf16 v[28:31], v[160:163], v[202:205], v[28:31]
	v_mfma_f32_16x16x32_bf16 v[20:23], v[152:155], v[210:213], v[20:23]
	v_mfma_f32_16x16x32_bf16 v[12:15], v[160:163], v[210:213], v[12:15]
	v_mfma_f32_16x16x32_bf16 v[60:63], v[156:159], v[188:191], v[60:63]
	v_mfma_f32_16x16x32_bf16 v[56:59], v[164:167], v[188:191], v[56:59]
	v_mfma_f32_16x16x32_bf16 v[52:55], v[156:159], v[196:199], v[52:55]
	v_mfma_f32_16x16x32_bf16 v[44:47], v[164:167], v[196:199], v[44:47]
	v_mfma_f32_16x16x32_bf16 v[36:39], v[156:159], v[206:209], v[36:39]
	v_mfma_f32_16x16x32_bf16 v[28:31], v[164:167], v[206:209], v[28:31]
	v_mfma_f32_16x16x32_bf16 v[20:23], v[156:159], v[214:217], v[20:23]
	v_mfma_f32_16x16x32_bf16 v[12:15], v[164:167], v[214:217], v[12:15]
	v_mfma_f32_16x16x32_bf16 v[48:51], v[168:171], v[184:187], v[48:51]
	v_mfma_f32_16x16x32_bf16 v[40:43], v[176:179], v[184:187], v[40:43]
	v_mfma_f32_16x16x32_bf16 v[32:35], v[168:171], v[192:195], v[32:35]
	v_mfma_f32_16x16x32_bf16 v[24:27], v[176:179], v[192:195], v[24:27]
	v_mfma_f32_16x16x32_bf16 v[16:19], v[168:171], v[202:205], v[16:19]
	v_mfma_f32_16x16x32_bf16 v[8:11], v[176:179], v[202:205], v[8:11]
	v_mfma_f32_16x16x32_bf16 v[4:7], v[168:171], v[210:213], v[4:7]
	v_mfma_f32_16x16x32_bf16 v[0:3], v[176:179], v[210:213], v[0:3]
	v_mfma_f32_16x16x32_bf16 v[48:51], v[172:175], v[188:191], v[48:51]
	v_mfma_f32_16x16x32_bf16 v[40:43], v[180:183], v[188:191], v[40:43]
	v_mfma_f32_16x16x32_bf16 v[32:35], v[172:175], v[196:199], v[32:35]
	v_mfma_f32_16x16x32_bf16 v[24:27], v[180:183], v[196:199], v[24:27]
	v_mfma_f32_16x16x32_bf16 v[16:19], v[172:175], v[206:209], v[16:19]
	v_mfma_f32_16x16x32_bf16 v[8:11], v[180:183], v[206:209], v[8:11]
	v_mfma_f32_16x16x32_bf16 v[4:7], v[172:175], v[214:217], v[4:7]
	v_mfma_f32_16x16x32_bf16 v[0:3], v[180:183], v[214:217], v[0:3]
	s_add_i32 s92, s92, 2
	s_add_u32 s58, s58, 0x100
	s_addc_u32 s59, s59, 0
	s_add_u32 s90, s90, 0x100
	s_addc_u32 s91, s91, 0
	s_cmp_gt_u32 s92, 13
	s_barrier
	s_cbranch_scc0 .LBB0_384
	s_setprio 0
	s_and_b64 vcc, exec, s[12:13]
	s_cbranch_vccz .LBB0_387
	s_barrier

.Lgp_729:
.LBB0_729:
	ds_read_b128 v[148:151], v145
	ds_read_b128 v[152:155], v145 offset:1024
	ds_read_b128 v[156:159], v145 offset:2048
	ds_read_b128 v[160:163], v145 offset:3072
	ds_read_b128 v[164:167], v146
	ds_read_b128 v[168:171], v146 offset:1024
	ds_read_b128 v[172:175], v146 offset:2048
	ds_read_b128 v[176:179], v146 offset:3072
	s_add_u32 s60, s58, 0xfffc0080
	s_addc_u32 s61, s59, -1
	s_cmp_eq_u32 s82, 12
	s_cselect_b32 s63, s45, s61
	s_cselect_b32 s62, s78, s60
	s_cselect_b32 s61, s35, s81
	s_cselect_b32 s60, s79, s80
	v_lshl_add_u64 v[140:141], s[58:59], 0, v[132:133]
	s_add_i32 m0, s67, 0xc000
	ds_read_b128 v[180:183], v147
	ds_read_b128 v[184:187], v147 offset:1024
	ds_read_b128 v[188:191], v147 offset:2048
	ds_read_b128 v[192:195], v147 offset:3072
	ds_read_b128 v[196:199], v147 offset:4096
	ds_read_b128 v[202:205], v147 offset:5120
	ds_read_b128 v[206:209], v147 offset:6144
	ds_read_b128 v[210:213], v147 offset:7168
	global_load_lds_dwordx4 v[140:141], off
	v_lshl_add_u64 v[140:141], s[58:59], 0, v[134:135]
	s_add_i32 m0, s67, 0xe000
	s_nop 0
	global_load_lds_dwordx4 v[140:141], off
	s_waitcnt vmcnt(8)
	s_waitcnt lgkmcnt(0)
	s_barrier
	s_waitcnt lgkmcnt(0)
	v_mfma_f32_16x16x32_bf16 v[124:127], v[148:151], v[180:183], v[124:127]
	v_mfma_f32_16x16x32_bf16 v[120:123], v[156:159], v[180:183], v[120:123]
	v_mfma_f32_16x16x32_bf16 v[112:115], v[148:151], v[188:191], v[112:115]
	v_mfma_f32_16x16x32_bf16 v[108:111], v[156:159], v[188:191], v[108:111]
	v_mfma_f32_16x16x32_bf16 v[96:99], v[148:151], v[196:199], v[96:99]
	v_mfma_f32_16x16x32_bf16 v[92:95], v[156:159], v[196:199], v[92:95]
	v_mfma_f32_16x16x32_bf16 v[80:83], v[148:151], v[206:209], v[80:83]
	v_mfma_f32_16x16x32_bf16 v[76:79], v[156:159], v[206:209], v[76:79]
	v_mfma_f32_16x16x32_bf16 v[124:127], v[152:155], v[184:187], v[124:127]
	v_mfma_f32_16x16x32_bf16 v[120:123], v[160:163], v[184:187], v[120:123]
	v_mfma_f32_16x16x32_bf16 v[112:115], v[152:155], v[192:195], v[112:115]
	v_mfma_f32_16x16x32_bf16 v[108:111], v[160:163], v[192:195], v[108:111]
	v_mfma_f32_16x16x32_bf16 v[96:99], v[152:155], v[202:205], v[96:99]
	v_mfma_f32_16x16x32_bf16 v[92:95], v[160:163], v[202:205], v[92:95]
	v_mfma_f32_16x16x32_bf16 v[80:83], v[152:155], v[210:213], v[80:83]
	v_mfma_f32_16x16x32_bf16 v[76:79], v[160:163], v[210:213], v[76:79]
	v_mfma_f32_16x16x32_bf16 v[116:119], v[164:167], v[180:183], v[116:119]
	v_mfma_f32_16x16x32_bf16 v[104:107], v[172:175], v[180:183], v[104:107]
	v_mfma_f32_16x16x32_bf16 v[100:103], v[164:167], v[188:191], v[100:103]
	v_mfma_f32_16x16x32_bf16 v[88:91], v[172:175], v[188:191], v[88:91]
	v_mfma_f32_16x16x32_bf16 v[84:87], v[164:167], v[196:199], v[84:87]
	v_mfma_f32_16x16x32_bf16 v[72:75], v[172:175], v[196:199], v[72:75]
	v_mfma_f32_16x16x32_bf16 v[68:71], v[164:167], v[206:209], v[68:71]
	v_mfma_f32_16x16x32_bf16 v[64:67], v[172:175], v[206:209], v[64:67]
	v_mfma_f32_16x16x32_bf16 v[116:119], v[168:171], v[184:187], v[116:119]
	v_mfma_f32_16x16x32_bf16 v[104:107], v[176:179], v[184:187], v[104:107]
	v_mfma_f32_16x16x32_bf16 v[100:103], v[168:171], v[192:195], v[100:103]
	v_mfma_f32_16x16x32_bf16 v[88:91], v[176:179], v[192:195], v[88:91]
	v_mfma_f32_16x16x32_bf16 v[84:87], v[168:171], v[202:205], v[84:87]
	v_mfma_f32_16x16x32_bf16 v[72:75], v[176:179], v[202:205], v[72:75]
	v_mfma_f32_16x16x32_bf16 v[68:71], v[168:171], v[210:213], v[68:71]
	v_mfma_f32_16x16x32_bf16 v[64:67], v[176:179], v[210:213], v[64:67]
	s_barrier
	s_add_i32 s83, s76, s66
	v_lshl_add_u64 v[140:141], s[60:61], 0, v[130:131]
	s_mov_b32 m0, s83
	ds_read_b128 v[180:183], v147 offset:16384
	ds_read_b128 v[184:187], v147 offset:17408
	ds_read_b128 v[188:191], v147 offset:18432
	ds_read_b128 v[192:195], v147 offset:19456
	ds_read_b128 v[196:199], v147 offset:20480
	ds_read_b128 v[202:205], v147 offset:21504
	ds_read_b128 v[206:209], v147 offset:22528
	ds_read_b128 v[210:213], v147 offset:23552
	global_load_lds_dwordx4 v[140:141], off
	s_add_i32 m0, s83, 0x2000
	s_add_u32 s84, s60, 0x40000
	v_lshl_add_u64 v[214:215], s[60:61], 0, v[128:129]
	s_addc_u32 s85, s61, 0
	s_add_i32 s83, s77, s66
	global_load_lds_dwordx4 v[214:215], off
	v_lshl_add_u64 v[216:217], s[84:85], 0, v[130:131]
	s_mov_b32 m0, s83
	v_lshl_add_u64 v[218:219], s[62:63], 0, v[128:129]
	global_load_lds_dwordx4 v[216:217], off
	v_lshl_add_u64 v[216:217], s[84:85], 0, v[128:129]
	s_add_i32 m0, s83, 0x2000
	s_nop 0
	global_load_lds_dwordx4 v[216:217], off
	v_lshl_add_u64 v[216:217], s[62:63], 0, v[130:131]
	s_mov_b32 m0, s67
	s_nop 0
	global_load_lds_dwordx4 v[216:217], off
	s_mov_b32 m0, s68
	s_nop 0
	global_load_lds_dwordx4 v[218:219], off
	s_waitcnt vmcnt(8)
	s_waitcnt lgkmcnt(0)
	s_barrier
	s_waitcnt lgkmcnt(0)
	v_mfma_f32_16x16x32_bf16 v[60:63], v[148:151], v[180:183], v[60:63]
	v_mfma_f32_16x16x32_bf16 v[56:59], v[156:159], v[180:183], v[56:59]
	v_mfma_f32_16x16x32_bf16 v[48:51], v[148:151], v[188:191], v[48:51]
	v_mfma_f32_16x16x32_bf16 v[44:47], v[156:159], v[188:191], v[44:47]
	v_mfma_f32_16x16x32_bf16 v[32:35], v[148:151], v[196:199], v[32:35]
	v_mfma_f32_16x16x32_bf16 v[28:31], v[156:159], v[196:199], v[28:31]
	v_mfma_f32_16x16x32_bf16 v[16:19], v[148:151], v[206:209], v[16:19]
	v_mfma_f32_16x16x32_bf16 v[12:15], v[156:159], v[206:209], v[12:15]
	v_mfma_f32_16x16x32_bf16 v[60:63], v[152:155], v[184:187], v[60:63]
	v_mfma_f32_16x16x32_bf16 v[56:59], v[160:163], v[184:187], v[56:59]
	v_mfma_f32_16x16x32_bf16 v[48:51], v[152:155], v[192:195], v[48:51]
	v_mfma_f32_16x16x32_bf16 v[44:47], v[160:163], v[192:195], v[44:47]
	v_mfma_f32_16x16x32_bf16 v[32:35], v[152:155], v[202:205], v[32:35]
	v_mfma_f32_16x16x32_bf16 v[28:31], v[160:163], v[202:205], v[28:31]
	v_mfma_f32_16x16x32_bf16 v[16:19], v[152:155], v[210:213], v[16:19]
	v_mfma_f32_16x16x32_bf16 v[12:15], v[160:163], v[210:213], v[12:15]
	v_mfma_f32_16x16x32_bf16 v[52:55], v[164:167], v[180:183], v[52:55]
	v_mfma_f32_16x16x32_bf16 v[40:43], v[172:175], v[180:183], v[40:43]
	v_mfma_f32_16x16x32_bf16 v[36:39], v[164:167], v[188:191], v[36:39]
	v_mfma_f32_16x16x32_bf16 v[24:27], v[172:175], v[188:191], v[24:27]
	v_mfma_f32_16x16x32_bf16 v[20:23], v[164:167], v[196:199], v[20:23]
	v_mfma_f32_16x16x32_bf16 v[8:11], v[172:175], v[196:199], v[8:11]
	v_mfma_f32_16x16x32_bf16 v[4:7], v[164:167], v[206:209], v[4:7]
	v_mfma_f32_16x16x32_bf16 v[0:3], v[172:175], v[206:209], v[0:3]
	v_mfma_f32_16x16x32_bf16 v[52:55], v[168:171], v[184:187], v[52:55]
	v_mfma_f32_16x16x32_bf16 v[40:43], v[176:179], v[184:187], v[40:43]
	v_mfma_f32_16x16x32_bf16 v[36:39], v[168:171], v[192:195], v[36:39]
	v_mfma_f32_16x16x32_bf16 v[24:27], v[176:179], v[192:195], v[24:27]
	v_mfma_f32_16x16x32_bf16 v[20:23], v[168:171], v[202:205], v[20:23]
	v_mfma_f32_16x16x32_bf16 v[8:11], v[176:179], v[202:205], v[8:11]
	v_mfma_f32_16x16x32_bf16 v[4:7], v[168:171], v[210:213], v[4:7]
	v_mfma_f32_16x16x32_bf16 v[0:3], v[176:179], v[210:213], v[0:3]
	s_barrier
	s_add_i32 s83, 0, 0x18000
	s_add_i32 s84, 0, 0x1c000
	v_add_u32_e32 v160, s83, v143
	v_add_u32_e32 v176, s84, v143
	ds_read_b128 v[148:151], v160
	ds_read_b128 v[152:155], v160 offset:1024
	ds_read_b128 v[156:159], v160 offset:2048
	ds_read_b128 v[160:163], v160 offset:3072
	ds_read_b128 v[164:167], v176
	ds_read_b128 v[168:171], v176 offset:1024
	ds_read_b128 v[172:175], v176 offset:2048
	ds_read_b128 v[176:179], v176 offset:3072
	s_add_u32 s62, s62, 0x40000
	s_addc_u32 s63, s63, 0
	s_mov_b32 m0, s69
	v_lshl_add_u64 v[220:221], s[62:63], 0, v[130:131]
	ds_read_b128 v[180:183], v147 offset:32768
	ds_read_b128 v[184:187], v147 offset:33792
	ds_read_b128 v[188:191], v147 offset:34816
	ds_read_b128 v[192:195], v147 offset:35840
	ds_read_b128 v[196:199], v147 offset:36864
	ds_read_b128 v[202:205], v147 offset:37888
	ds_read_b128 v[206:209], v147 offset:38912
	ds_read_b128 v[210:213], v147 offset:39936
	global_load_lds_dwordx4 v[220:221], off
	v_lshl_add_u64 v[220:221], s[62:63], 0, v[128:129]
	s_mov_b32 m0, s70
	s_nop 0
	global_load_lds_dwordx4 v[220:221], off
	s_waitcnt vmcnt(8)
	s_waitcnt lgkmcnt(0)
	s_barrier
	s_waitcnt lgkmcnt(0)
	v_mfma_f32_16x16x32_bf16 v[124:127], v[148:151], v[180:183], v[124:127]
	v_mfma_f32_16x16x32_bf16 v[120:123], v[156:159], v[180:183], v[120:123]
	v_mfma_f32_16x16x32_bf16 v[112:115], v[148:151], v[188:191], v[112:115]
	v_mfma_f32_16x16x32_bf16 v[108:111], v[156:159], v[188:191], v[108:111]
	v_mfma_f32_16x16x32_bf16 v[96:99], v[148:151], v[196:199], v[96:99]
	v_mfma_f32_16x16x32_bf16 v[92:95], v[156:159], v[196:199], v[92:95]
	v_mfma_f32_16x16x32_bf16 v[80:83], v[148:151], v[206:209], v[80:83]
	v_mfma_f32_16x16x32_bf16 v[76:79], v[156:159], v[206:209], v[76:79]
	v_mfma_f32_16x16x32_bf16 v[124:127], v[152:155], v[184:187], v[124:127]
	v_mfma_f32_16x16x32_bf16 v[120:123], v[160:163], v[184:187], v[120:123]
	v_mfma_f32_16x16x32_bf16 v[112:115], v[152:155], v[192:195], v[112:115]
	v_mfma_f32_16x16x32_bf16 v[108:111], v[160:163], v[192:195], v[108:111]
	v_mfma_f32_16x16x32_bf16 v[96:99], v[152:155], v[202:205], v[96:99]
	v_mfma_f32_16x16x32_bf16 v[92:95], v[160:163], v[202:205], v[92:95]
	v_mfma_f32_16x16x32_bf16 v[80:83], v[152:155], v[210:213], v[80:83]
	v_mfma_f32_16x16x32_bf16 v[76:79], v[160:163], v[210:213], v[76:79]
	v_mfma_f32_16x16x32_bf16 v[116:119], v[164:167], v[180:183], v[116:119]
	v_mfma_f32_16x16x32_bf16 v[104:107], v[172:175], v[180:183], v[104:107]
	v_mfma_f32_16x16x32_bf16 v[100:103], v[164:167], v[188:191], v[100:103]
	v_mfma_f32_16x16x32_bf16 v[88:91], v[172:175], v[188:191], v[88:91]
	v_mfma_f32_16x16x32_bf16 v[84:87], v[164:167], v[196:199], v[84:87]
	v_mfma_f32_16x16x32_bf16 v[72:75], v[172:175], v[196:199], v[72:75]
	v_mfma_f32_16x16x32_bf16 v[68:71], v[164:167], v[206:209], v[68:71]
	v_mfma_f32_16x16x32_bf16 v[64:67], v[172:175], v[206:209], v[64:67]
	v_mfma_f32_16x16x32_bf16 v[116:119], v[168:171], v[184:187], v[116:119]
	v_mfma_f32_16x16x32_bf16 v[104:107], v[176:179], v[184:187], v[104:107]
	v_mfma_f32_16x16x32_bf16 v[100:103], v[168:171], v[192:195], v[100:103]
	v_mfma_f32_16x16x32_bf16 v[88:91], v[176:179], v[192:195], v[88:91]
	v_mfma_f32_16x16x32_bf16 v[84:87], v[168:171], v[202:205], v[84:87]
	v_mfma_f32_16x16x32_bf16 v[72:75], v[176:179], v[202:205], v[72:75]
	v_mfma_f32_16x16x32_bf16 v[68:71], v[168:171], v[210:213], v[68:71]
	v_mfma_f32_16x16x32_bf16 v[64:67], v[176:179], v[210:213], v[64:67]
	s_barrier
	s_add_i32 s62, s83, s66
	v_lshl_add_u64 v[140:141], v[140:141], 0, s[6:7]
	s_mov_b32 m0, s62
	ds_read_b128 v[180:183], v147 offset:49152
	ds_read_b128 v[184:187], v147 offset:50176
	ds_read_b128 v[188:191], v147 offset:51200
	ds_read_b128 v[192:195], v147 offset:52224
	ds_read_b128 v[196:199], v147 offset:53248
	ds_read_b128 v[202:205], v147 offset:54272
	ds_read_b128 v[206:209], v147 offset:55296
	ds_read_b128 v[210:213], v147 offset:56320
	global_load_lds_dwordx4 v[140:141], off
	s_add_i32 m0, s62, 0x2000
	s_add_u32 s60, s60, 0x40080
	v_lshl_add_u64 v[140:141], v[214:215], 0, s[6:7]
	s_addc_u32 s61, s61, 0
	s_add_i32 s62, s84, s66
	global_load_lds_dwordx4 v[140:141], off
	v_lshl_add_u64 v[140:141], s[60:61], 0, v[130:131]
	s_mov_b32 m0, s62
	s_nop 0
	global_load_lds_dwordx4 v[140:141], off
	v_lshl_add_u64 v[140:141], s[60:61], 0, v[128:129]
	s_add_i32 m0, s62, 0x2000
	s_nop 0
	global_load_lds_dwordx4 v[140:141], off
	v_lshl_add_u64 v[140:141], v[216:217], 0, s[6:7]
	s_mov_b32 m0, s72
	s_nop 0
	global_load_lds_dwordx4 v[140:141], off
	v_lshl_add_u64 v[140:141], v[218:219], 0, s[6:7]
	s_mov_b32 m0, s73
	s_nop 0
	global_load_lds_dwordx4 v[140:141], off
	s_waitcnt vmcnt(8)
	s_waitcnt lgkmcnt(0)
	s_barrier
	s_waitcnt lgkmcnt(0)
	v_mfma_f32_16x16x32_bf16 v[60:63], v[148:151], v[180:183], v[60:63]
	v_mfma_f32_16x16x32_bf16 v[56:59], v[156:159], v[180:183], v[56:59]
	v_mfma_f32_16x16x32_bf16 v[48:51], v[148:151], v[188:191], v[48:51]
	v_mfma_f32_16x16x32_bf16 v[44:47], v[156:159], v[188:191], v[44:47]
	v_mfma_f32_16x16x32_bf16 v[32:35], v[148:151], v[196:199], v[32:35]
	v_mfma_f32_16x16x32_bf16 v[28:31], v[156:159], v[196:199], v[28:31]
	v_mfma_f32_16x16x32_bf16 v[16:19], v[148:151], v[206:209], v[16:19]
	v_mfma_f32_16x16x32_bf16 v[12:15], v[156:159], v[206:209], v[12:15]
	v_mfma_f32_16x16x32_bf16 v[60:63], v[152:155], v[184:187], v[60:63]
	v_mfma_f32_16x16x32_bf16 v[56:59], v[160:163], v[184:187], v[56:59]
	v_mfma_f32_16x16x32_bf16 v[48:51], v[152:155], v[192:195], v[48:51]
	v_mfma_f32_16x16x32_bf16 v[44:47], v[160:163], v[192:195], v[44:47]
	v_mfma_f32_16x16x32_bf16 v[32:35], v[152:155], v[202:205], v[32:35]
	v_mfma_f32_16x16x32_bf16 v[28:31], v[160:163], v[202:205], v[28:31]
	v_mfma_f32_16x16x32_bf16 v[16:19], v[152:155], v[210:213], v[16:19]
	v_mfma_f32_16x16x32_bf16 v[12:15], v[160:163], v[210:213], v[12:15]
	v_mfma_f32_16x16x32_bf16 v[52:55], v[164:167], v[180:183], v[52:55]
	v_mfma_f32_16x16x32_bf16 v[40:43], v[172:175], v[180:183], v[40:43]
	v_mfma_f32_16x16x32_bf16 v[36:39], v[164:167], v[188:191], v[36:39]
	v_mfma_f32_16x16x32_bf16 v[24:27], v[172:175], v[188:191], v[24:27]
	v_mfma_f32_16x16x32_bf16 v[20:23], v[164:167], v[196:199], v[20:23]
	v_mfma_f32_16x16x32_bf16 v[8:11], v[172:175], v[196:199], v[8:11]
	v_mfma_f32_16x16x32_bf16 v[4:7], v[164:167], v[206:209], v[4:7]
	v_mfma_f32_16x16x32_bf16 v[0:3], v[172:175], v[206:209], v[0:3]
	v_mfma_f32_16x16x32_bf16 v[52:55], v[168:171], v[184:187], v[52:55]
	v_mfma_f32_16x16x32_bf16 v[40:43], v[176:179], v[184:187], v[40:43]
	v_mfma_f32_16x16x32_bf16 v[36:39], v[168:171], v[192:195], v[36:39]
	v_mfma_f32_16x16x32_bf16 v[24:27], v[176:179], v[192:195], v[24:27]
	v_mfma_f32_16x16x32_bf16 v[20:23], v[168:171], v[202:205], v[20:23]
	v_mfma_f32_16x16x32_bf16 v[8:11], v[176:179], v[202:205], v[8:11]
	v_mfma_f32_16x16x32_bf16 v[4:7], v[168:171], v[210:213], v[4:7]
	v_mfma_f32_16x16x32_bf16 v[0:3], v[176:179], v[210:213], v[0:3]
	s_add_i32 s82, s82, 2
	s_add_u32 s58, s58, 0x100
	s_addc_u32 s59, s59, 0
	s_add_u32 s80, s80, 0x100
	s_addc_u32 s81, s81, 0
	s_cmp_gt_u32 s82, 13
	s_barrier
	s_cbranch_scc0 .LBB0_729
	s_setprio 0
	s_and_b64 vcc, exec, s[8:9]
	s_cbranch_vccz .LBB0_732
	s_barrier

.Lgp_866:
.LBB0_866:
	ds_read_b128 v[64:67], v203
	ds_read_b128 v[68:71], v203 offset:1024
	ds_read_b128 v[72:75], v203 offset:2048
	ds_read_b128 v[76:79], v203 offset:3072
	ds_read_b128 v[80:83], v204
	ds_read_b128 v[84:87], v204 offset:1024
	ds_read_b128 v[88:91], v204 offset:2048
	ds_read_b128 v[92:95], v204 offset:3072
	s_add_u32 s64, s62, 0xfffc0080
	s_addc_u32 s65, s63, -1
	s_cmp_eq_u32 s90, 12
	s_cselect_b32 s67, s55, s65
	s_cselect_b32 s66, s86, s64
	s_cselect_b32 s65, s53, s89
	s_cselect_b32 s64, s87, s88
	v_lshl_add_u64 v[220:221], s[62:63], 0, v[172:173]
	s_add_i32 m0, s73, 0xc000
	ds_read_b128 v[180:183], v205
	ds_read_b128 v[184:187], v205 offset:1024
	ds_read_b128 v[188:191], v205 offset:2048
	ds_read_b128 v[192:195], v205 offset:3072
	ds_read_b128 v[196:199], v205 offset:4096
	ds_read_b128 v[208:211], v205 offset:5120
	ds_read_b128 v[212:215], v205 offset:6144
	ds_read_b128 v[216:219], v205 offset:7168
	global_load_lds_dwordx4 v[220:221], off
	v_lshl_add_u64 v[220:221], s[62:63], 0, v[174:175]
	s_add_i32 m0, s73, 0xe000
	s_nop 0
	global_load_lds_dwordx4 v[220:221], off
	s_waitcnt vmcnt(8)
	s_waitcnt lgkmcnt(0)
	s_barrier
	s_waitcnt lgkmcnt(0)
	v_mfma_f32_16x16x32_bf16 v[148:151], v[64:67], v[180:183], v[148:151]
	v_mfma_f32_16x16x32_bf16 v[144:147], v[72:75], v[180:183], v[144:147]
	v_mfma_f32_16x16x32_bf16 v[132:135], v[64:67], v[188:191], v[132:135]
	v_mfma_f32_16x16x32_bf16 v[128:131], v[72:75], v[188:191], v[128:131]
	v_mfma_f32_16x16x32_bf16 v[116:119], v[64:67], v[196:199], v[116:119]
	v_mfma_f32_16x16x32_bf16 v[112:115], v[72:75], v[196:199], v[112:115]
	v_mfma_f32_16x16x32_bf16 v[104:107], v[64:67], v[212:215], v[104:107]
	v_mfma_f32_16x16x32_bf16 v[100:103], v[72:75], v[212:215], v[100:103]
	v_mfma_f32_16x16x32_bf16 v[148:151], v[68:71], v[184:187], v[148:151]
	v_mfma_f32_16x16x32_bf16 v[144:147], v[76:79], v[184:187], v[144:147]
	v_mfma_f32_16x16x32_bf16 v[132:135], v[68:71], v[192:195], v[132:135]
	v_mfma_f32_16x16x32_bf16 v[128:131], v[76:79], v[192:195], v[128:131]
	v_mfma_f32_16x16x32_bf16 v[116:119], v[68:71], v[208:211], v[116:119]
	v_mfma_f32_16x16x32_bf16 v[112:115], v[76:79], v[208:211], v[112:115]
	v_mfma_f32_16x16x32_bf16 v[104:107], v[68:71], v[216:219], v[104:107]
	v_mfma_f32_16x16x32_bf16 v[100:103], v[76:79], v[216:219], v[100:103]
	v_mfma_f32_16x16x32_bf16 v[152:155], v[80:83], v[180:183], v[152:155]
	v_mfma_f32_16x16x32_bf16 v[156:159], v[88:91], v[180:183], v[156:159]
	v_mfma_f32_16x16x32_bf16 v[136:139], v[80:83], v[188:191], v[136:139]
	v_mfma_f32_16x16x32_bf16 v[140:143], v[88:91], v[188:191], v[140:143]
	v_mfma_f32_16x16x32_bf16 v[120:123], v[80:83], v[196:199], v[120:123]
	v_mfma_f32_16x16x32_bf16 v[124:127], v[88:91], v[196:199], v[124:127]
	v_mfma_f32_16x16x32_bf16 v[96:99], v[80:83], v[212:215], v[96:99]
	v_mfma_f32_16x16x32_bf16 v[108:111], v[88:91], v[212:215], v[108:111]
	v_mfma_f32_16x16x32_bf16 v[152:155], v[84:87], v[184:187], v[152:155]
	v_mfma_f32_16x16x32_bf16 v[156:159], v[92:95], v[184:187], v[156:159]
	v_mfma_f32_16x16x32_bf16 v[136:139], v[84:87], v[192:195], v[136:139]
	v_mfma_f32_16x16x32_bf16 v[140:143], v[92:95], v[192:195], v[140:143]
	v_mfma_f32_16x16x32_bf16 v[120:123], v[84:87], v[208:211], v[120:123]
	v_mfma_f32_16x16x32_bf16 v[124:127], v[92:95], v[208:211], v[124:127]
	v_mfma_f32_16x16x32_bf16 v[96:99], v[84:87], v[216:219], v[96:99]
	v_mfma_f32_16x16x32_bf16 v[108:111], v[92:95], v[216:219], v[108:111]
	s_barrier
	s_add_i32 s91, s82, s72
	v_lshl_add_u64 v[220:221], s[64:65], 0, v[164:165]
	s_mov_b32 m0, s91
	ds_read_b128 v[180:183], v205 offset:16384
	ds_read_b128 v[184:187], v205 offset:17408
	ds_read_b128 v[188:191], v205 offset:18432
	ds_read_b128 v[192:195], v205 offset:19456
	ds_read_b128 v[196:199], v205 offset:20480
	ds_read_b128 v[208:211], v205 offset:21504
	ds_read_b128 v[212:215], v205 offset:22528
	ds_read_b128 v[216:219], v205 offset:23552
	global_load_lds_dwordx4 v[220:221], off
	s_add_i32 m0, s91, 0x2000
	s_add_u32 s92, s64, 0x40000
	v_lshl_add_u64 v[222:223], s[64:65], 0, v[160:161]
	s_addc_u32 s93, s65, 0
	s_add_i32 s91, s83, s72
	global_load_lds_dwordx4 v[222:223], off
	v_lshl_add_u64 v[224:225], s[92:93], 0, v[164:165]
	s_mov_b32 m0, s91
	v_lshl_add_u64 v[226:227], s[66:67], 0, v[162:163]
	global_load_lds_dwordx4 v[224:225], off
	v_lshl_add_u64 v[224:225], s[92:93], 0, v[160:161]
	s_add_i32 m0, s91, 0x2000
	s_nop 0
	global_load_lds_dwordx4 v[224:225], off
	v_lshl_add_u64 v[224:225], s[66:67], 0, v[166:167]
	s_mov_b32 m0, s73
	s_nop 0
	global_load_lds_dwordx4 v[224:225], off
	s_mov_b32 m0, s74
	s_nop 0
	global_load_lds_dwordx4 v[226:227], off
	s_waitcnt vmcnt(8)
	s_waitcnt lgkmcnt(0)
	s_barrier
	s_waitcnt lgkmcnt(0)
	v_mfma_f32_16x16x32_bf16 v[52:55], v[64:67], v[180:183], v[52:55]
	v_mfma_f32_16x16x32_bf16 v[48:51], v[72:75], v[180:183], v[48:51]
	v_mfma_f32_16x16x32_bf16 v[36:39], v[64:67], v[188:191], v[36:39]
	v_mfma_f32_16x16x32_bf16 v[32:35], v[72:75], v[188:191], v[32:35]
	v_mfma_f32_16x16x32_bf16 v[20:23], v[64:67], v[196:199], v[20:23]
	v_mfma_f32_16x16x32_bf16 v[16:19], v[72:75], v[196:199], v[16:19]
	v_mfma_f32_16x16x32_bf16 v[8:11], v[64:67], v[212:215], v[8:11]
	v_mfma_f32_16x16x32_bf16 v[4:7], v[72:75], v[212:215], v[4:7]
	v_mfma_f32_16x16x32_bf16 v[52:55], v[68:71], v[184:187], v[52:55]
	v_mfma_f32_16x16x32_bf16 v[48:51], v[76:79], v[184:187], v[48:51]
	v_mfma_f32_16x16x32_bf16 v[36:39], v[68:71], v[192:195], v[36:39]
	v_mfma_f32_16x16x32_bf16 v[32:35], v[76:79], v[192:195], v[32:35]
	v_mfma_f32_16x16x32_bf16 v[20:23], v[68:71], v[208:211], v[20:23]
	v_mfma_f32_16x16x32_bf16 v[16:19], v[76:79], v[208:211], v[16:19]
	v_mfma_f32_16x16x32_bf16 v[8:11], v[68:71], v[216:219], v[8:11]
	v_mfma_f32_16x16x32_bf16 v[4:7], v[76:79], v[216:219], v[4:7]
	v_mfma_f32_16x16x32_bf16 v[56:59], v[80:83], v[180:183], v[56:59]
	v_mfma_f32_16x16x32_bf16 v[60:63], v[88:91], v[180:183], v[60:63]
	v_mfma_f32_16x16x32_bf16 v[40:43], v[80:83], v[188:191], v[40:43]
	v_mfma_f32_16x16x32_bf16 v[44:47], v[88:91], v[188:191], v[44:47]
	v_mfma_f32_16x16x32_bf16 v[24:27], v[80:83], v[196:199], v[24:27]
	v_mfma_f32_16x16x32_bf16 v[28:31], v[88:91], v[196:199], v[28:31]
	v_mfma_f32_16x16x32_bf16 v[0:3], v[80:83], v[212:215], v[0:3]
	v_mfma_f32_16x16x32_bf16 v[12:15], v[88:91], v[212:215], v[12:15]
	v_mfma_f32_16x16x32_bf16 v[56:59], v[84:87], v[184:187], v[56:59]
	v_mfma_f32_16x16x32_bf16 v[60:63], v[92:95], v[184:187], v[60:63]
	v_mfma_f32_16x16x32_bf16 v[40:43], v[84:87], v[192:195], v[40:43]
	v_mfma_f32_16x16x32_bf16 v[44:47], v[92:95], v[192:195], v[44:47]
	v_mfma_f32_16x16x32_bf16 v[24:27], v[84:87], v[208:211], v[24:27]
	v_mfma_f32_16x16x32_bf16 v[28:31], v[92:95], v[208:211], v[28:31]
	v_mfma_f32_16x16x32_bf16 v[0:3], v[84:87], v[216:219], v[0:3]
	v_mfma_f32_16x16x32_bf16 v[12:15], v[92:95], v[216:219], v[12:15]
	s_barrier
	s_add_i32 s91, 0, 0x18000
	s_add_i32 s92, 0, 0x1c000
	v_add_u32_e32 v76, s91, v201
	v_add_u32_e32 v92, s92, v201
	ds_read_b128 v[64:67], v76
	ds_read_b128 v[68:71], v76 offset:1024
	ds_read_b128 v[72:75], v76 offset:2048
	ds_read_b128 v[76:79], v76 offset:3072
	ds_read_b128 v[80:83], v92
	ds_read_b128 v[84:87], v92 offset:1024
	ds_read_b128 v[88:91], v92 offset:2048
	ds_read_b128 v[92:95], v92 offset:3072
	s_add_u32 s66, s66, 0x40000
	s_addc_u32 s67, s67, 0
	s_mov_b32 m0, s75
	v_lshl_add_u64 v[228:229], s[66:67], 0, v[166:167]
	ds_read_b128 v[180:183], v205 offset:32768
	ds_read_b128 v[184:187], v205 offset:33792
	ds_read_b128 v[188:191], v205 offset:34816
	ds_read_b128 v[192:195], v205 offset:35840
	ds_read_b128 v[196:199], v205 offset:36864
	ds_read_b128 v[208:211], v205 offset:37888
	ds_read_b128 v[212:215], v205 offset:38912
	ds_read_b128 v[216:219], v205 offset:39936
	global_load_lds_dwordx4 v[228:229], off
	v_lshl_add_u64 v[228:229], s[66:67], 0, v[162:163]
	s_mov_b32 m0, s76
	s_nop 0
	global_load_lds_dwordx4 v[228:229], off
	s_waitcnt vmcnt(8)
	s_waitcnt lgkmcnt(0)
	s_barrier
	s_waitcnt lgkmcnt(0)
	v_mfma_f32_16x16x32_bf16 v[148:151], v[64:67], v[180:183], v[148:151]
	v_mfma_f32_16x16x32_bf16 v[144:147], v[72:75], v[180:183], v[144:147]
	v_mfma_f32_16x16x32_bf16 v[132:135], v[64:67], v[188:191], v[132:135]
	v_mfma_f32_16x16x32_bf16 v[128:131], v[72:75], v[188:191], v[128:131]
	v_mfma_f32_16x16x32_bf16 v[116:119], v[64:67], v[196:199], v[116:119]
	v_mfma_f32_16x16x32_bf16 v[112:115], v[72:75], v[196:199], v[112:115]
	v_mfma_f32_16x16x32_bf16 v[104:107], v[64:67], v[212:215], v[104:107]
	v_mfma_f32_16x16x32_bf16 v[100:103], v[72:75], v[212:215], v[100:103]
	v_mfma_f32_16x16x32_bf16 v[148:151], v[68:71], v[184:187], v[148:151]
	v_mfma_f32_16x16x32_bf16 v[144:147], v[76:79], v[184:187], v[144:147]
	v_mfma_f32_16x16x32_bf16 v[132:135], v[68:71], v[192:195], v[132:135]
	v_mfma_f32_16x16x32_bf16 v[128:131], v[76:79], v[192:195], v[128:131]
	v_mfma_f32_16x16x32_bf16 v[116:119], v[68:71], v[208:211], v[116:119]
	v_mfma_f32_16x16x32_bf16 v[112:115], v[76:79], v[208:211], v[112:115]
	v_mfma_f32_16x16x32_bf16 v[104:107], v[68:71], v[216:219], v[104:107]
	v_mfma_f32_16x16x32_bf16 v[100:103], v[76:79], v[216:219], v[100:103]
	v_mfma_f32_16x16x32_bf16 v[152:155], v[80:83], v[180:183], v[152:155]
	v_mfma_f32_16x16x32_bf16 v[156:159], v[88:91], v[180:183], v[156:159]
	v_mfma_f32_16x16x32_bf16 v[136:139], v[80:83], v[188:191], v[136:139]
	v_mfma_f32_16x16x32_bf16 v[140:143], v[88:91], v[188:191], v[140:143]
	v_mfma_f32_16x16x32_bf16 v[120:123], v[80:83], v[196:199], v[120:123]
	v_mfma_f32_16x16x32_bf16 v[124:127], v[88:91], v[196:199], v[124:127]
	v_mfma_f32_16x16x32_bf16 v[96:99], v[80:83], v[212:215], v[96:99]
	v_mfma_f32_16x16x32_bf16 v[108:111], v[88:91], v[212:215], v[108:111]
	v_mfma_f32_16x16x32_bf16 v[152:155], v[84:87], v[184:187], v[152:155]
	v_mfma_f32_16x16x32_bf16 v[156:159], v[92:95], v[184:187], v[156:159]
	v_mfma_f32_16x16x32_bf16 v[136:139], v[84:87], v[192:195], v[136:139]
	v_mfma_f32_16x16x32_bf16 v[140:143], v[92:95], v[192:195], v[140:143]
	v_mfma_f32_16x16x32_bf16 v[120:123], v[84:87], v[208:211], v[120:123]
	v_mfma_f32_16x16x32_bf16 v[124:127], v[92:95], v[208:211], v[124:127]
	v_mfma_f32_16x16x32_bf16 v[96:99], v[84:87], v[216:219], v[96:99]
	v_mfma_f32_16x16x32_bf16 v[108:111], v[92:95], v[216:219], v[108:111]
	s_barrier
	s_add_i32 s66, s91, s72
	v_lshl_add_u64 v[220:221], v[220:221], 0, s[20:21]
	s_mov_b32 m0, s66
	ds_read_b128 v[180:183], v205 offset:49152
	ds_read_b128 v[184:187], v205 offset:50176
	ds_read_b128 v[188:191], v205 offset:51200
	ds_read_b128 v[192:195], v205 offset:52224
	ds_read_b128 v[196:199], v205 offset:53248
	ds_read_b128 v[208:211], v205 offset:54272
	ds_read_b128 v[212:215], v205 offset:55296
	ds_read_b128 v[216:219], v205 offset:56320
	global_load_lds_dwordx4 v[220:221], off
	s_add_i32 m0, s66, 0x2000
	s_add_u32 s64, s64, 0x40080
	v_lshl_add_u64 v[220:221], v[222:223], 0, s[20:21]
	s_addc_u32 s65, s65, 0
	s_add_i32 s66, s92, s72
	global_load_lds_dwordx4 v[220:221], off
	v_lshl_add_u64 v[220:221], s[64:65], 0, v[164:165]
	s_mov_b32 m0, s66
	s_nop 0
	global_load_lds_dwordx4 v[220:221], off
	v_lshl_add_u64 v[220:221], s[64:65], 0, v[160:161]
	s_add_i32 m0, s66, 0x2000
	s_nop 0
	global_load_lds_dwordx4 v[220:221], off
	v_lshl_add_u64 v[220:221], v[224:225], 0, s[20:21]
	s_mov_b32 m0, s78
	s_nop 0
	global_load_lds_dwordx4 v[220:221], off
	v_lshl_add_u64 v[220:221], v[226:227], 0, s[20:21]
	s_mov_b32 m0, s79
	s_nop 0
	global_load_lds_dwordx4 v[220:221], off
	s_waitcnt vmcnt(8)
	s_waitcnt lgkmcnt(0)
	s_barrier
	s_waitcnt lgkmcnt(0)
	v_mfma_f32_16x16x32_bf16 v[52:55], v[64:67], v[180:183], v[52:55]
	v_mfma_f32_16x16x32_bf16 v[48:51], v[72:75], v[180:183], v[48:51]
	v_mfma_f32_16x16x32_bf16 v[36:39], v[64:67], v[188:191], v[36:39]
	v_mfma_f32_16x16x32_bf16 v[32:35], v[72:75], v[188:191], v[32:35]
	v_mfma_f32_16x16x32_bf16 v[20:23], v[64:67], v[196:199], v[20:23]
	v_mfma_f32_16x16x32_bf16 v[16:19], v[72:75], v[196:199], v[16:19]
	v_mfma_f32_16x16x32_bf16 v[8:11], v[64:67], v[212:215], v[8:11]
	v_mfma_f32_16x16x32_bf16 v[4:7], v[72:75], v[212:215], v[4:7]
	v_mfma_f32_16x16x32_bf16 v[52:55], v[68:71], v[184:187], v[52:55]
	v_mfma_f32_16x16x32_bf16 v[48:51], v[76:79], v[184:187], v[48:51]
	v_mfma_f32_16x16x32_bf16 v[36:39], v[68:71], v[192:195], v[36:39]
	v_mfma_f32_16x16x32_bf16 v[32:35], v[76:79], v[192:195], v[32:35]
	v_mfma_f32_16x16x32_bf16 v[20:23], v[68:71], v[208:211], v[20:23]
	v_mfma_f32_16x16x32_bf16 v[16:19], v[76:79], v[208:211], v[16:19]
	v_mfma_f32_16x16x32_bf16 v[8:11], v[68:71], v[216:219], v[8:11]
	v_mfma_f32_16x16x32_bf16 v[4:7], v[76:79], v[216:219], v[4:7]
	v_mfma_f32_16x16x32_bf16 v[56:59], v[80:83], v[180:183], v[56:59]
	v_mfma_f32_16x16x32_bf16 v[60:63], v[88:91], v[180:183], v[60:63]
	v_mfma_f32_16x16x32_bf16 v[40:43], v[80:83], v[188:191], v[40:43]
	v_mfma_f32_16x16x32_bf16 v[44:47], v[88:91], v[188:191], v[44:47]
	v_mfma_f32_16x16x32_bf16 v[24:27], v[80:83], v[196:199], v[24:27]
	v_mfma_f32_16x16x32_bf16 v[28:31], v[88:91], v[196:199], v[28:31]
	v_mfma_f32_16x16x32_bf16 v[0:3], v[80:83], v[212:215], v[0:3]
	v_mfma_f32_16x16x32_bf16 v[12:15], v[88:91], v[212:215], v[12:15]
	v_mfma_f32_16x16x32_bf16 v[56:59], v[84:87], v[184:187], v[56:59]
	v_mfma_f32_16x16x32_bf16 v[60:63], v[92:95], v[184:187], v[60:63]
	v_mfma_f32_16x16x32_bf16 v[40:43], v[84:87], v[192:195], v[40:43]
	v_mfma_f32_16x16x32_bf16 v[44:47], v[92:95], v[192:195], v[44:47]
	v_mfma_f32_16x16x32_bf16 v[24:27], v[84:87], v[208:211], v[24:27]
	v_mfma_f32_16x16x32_bf16 v[28:31], v[92:95], v[208:211], v[28:31]
	v_mfma_f32_16x16x32_bf16 v[0:3], v[84:87], v[216:219], v[0:3]
	v_mfma_f32_16x16x32_bf16 v[12:15], v[92:95], v[216:219], v[12:15]
	s_add_i32 s90, s90, 2
	s_add_u32 s62, s62, 0x100
	s_addc_u32 s63, s63, 0
	s_add_u32 s88, s88, 0x100
	s_addc_u32 s89, s89, 0
	s_cmp_gt_u32 s90, 13
	s_barrier
	s_cbranch_scc0 .LBB0_866
	s_setprio 0
	s_and_b64 vcc, exec, s[34:35]
	s_cbranch_vccz .LBB0_869
	s_barrier

.Lgp_1018:
.LBB0_1018:
	ds_read_b128 v[140:143], v149
	ds_read_b128 v[152:155], v149 offset:1024
	ds_read_b128 v[156:159], v149 offset:2048
	ds_read_b128 v[160:163], v149 offset:3072
	ds_read_b128 v[164:167], v150
	ds_read_b128 v[168:171], v150 offset:1024
	ds_read_b128 v[172:175], v150 offset:2048
	ds_read_b128 v[176:179], v150 offset:3072
	s_add_u32 s54, s52, 0xfff50080
	s_addc_u32 s55, s53, -1
	s_cmp_eq_u32 s78, 40
	s_cselect_b32 s59, s5, s55
	s_cselect_b32 s58, s4, s54
	s_cselect_b32 s55, s51, s77
	s_cselect_b32 s54, s50, s76
	v_lshl_add_u64 v[144:145], s[52:53], 0, v[132:133]
	s_add_i32 m0, s63, 0xc000
	ds_read_b128 v[180:183], v151
	ds_read_b128 v[184:187], v151 offset:1024
	ds_read_b128 v[188:191], v151 offset:2048
	ds_read_b128 v[192:195], v151 offset:3072
	ds_read_b128 v[196:199], v151 offset:4096
	ds_read_b128 v[202:205], v151 offset:5120
	ds_read_b128 v[206:209], v151 offset:6144
	ds_read_b128 v[210:213], v151 offset:7168
	global_load_lds_dwordx4 v[144:145], off
	v_lshl_add_u64 v[144:145], s[52:53], 0, v[134:135]
	s_add_i32 m0, s63, 0xe000
	s_nop 0
	global_load_lds_dwordx4 v[144:145], off
	s_waitcnt vmcnt(8)
	s_waitcnt lgkmcnt(0)
	s_barrier
	s_waitcnt lgkmcnt(0)
	v_mfma_f32_16x16x32_bf16 v[124:127], v[140:143], v[180:183], v[124:127]
	v_mfma_f32_16x16x32_bf16 v[120:123], v[156:159], v[180:183], v[120:123]
	v_mfma_f32_16x16x32_bf16 v[112:115], v[140:143], v[188:191], v[112:115]
	v_mfma_f32_16x16x32_bf16 v[104:107], v[156:159], v[188:191], v[104:107]
	v_mfma_f32_16x16x32_bf16 v[96:99], v[140:143], v[196:199], v[96:99]
	v_mfma_f32_16x16x32_bf16 v[88:91], v[156:159], v[196:199], v[88:91]
	v_mfma_f32_16x16x32_bf16 v[80:83], v[140:143], v[206:209], v[80:83]
	v_mfma_f32_16x16x32_bf16 v[72:75], v[156:159], v[206:209], v[72:75]
	v_mfma_f32_16x16x32_bf16 v[124:127], v[152:155], v[184:187], v[124:127]
	v_mfma_f32_16x16x32_bf16 v[120:123], v[160:163], v[184:187], v[120:123]
	v_mfma_f32_16x16x32_bf16 v[112:115], v[152:155], v[192:195], v[112:115]
	v_mfma_f32_16x16x32_bf16 v[104:107], v[160:163], v[192:195], v[104:107]
	v_mfma_f32_16x16x32_bf16 v[96:99], v[152:155], v[202:205], v[96:99]
	v_mfma_f32_16x16x32_bf16 v[88:91], v[160:163], v[202:205], v[88:91]
	v_mfma_f32_16x16x32_bf16 v[80:83], v[152:155], v[210:213], v[80:83]
	v_mfma_f32_16x16x32_bf16 v[72:75], v[160:163], v[210:213], v[72:75]
	v_mfma_f32_16x16x32_bf16 v[116:119], v[164:167], v[180:183], v[116:119]
	v_mfma_f32_16x16x32_bf16 v[108:111], v[172:175], v[180:183], v[108:111]
	v_mfma_f32_16x16x32_bf16 v[100:103], v[164:167], v[188:191], v[100:103]
	v_mfma_f32_16x16x32_bf16 v[92:95], v[172:175], v[188:191], v[92:95]
	v_mfma_f32_16x16x32_bf16 v[84:87], v[164:167], v[196:199], v[84:87]
	v_mfma_f32_16x16x32_bf16 v[76:79], v[172:175], v[196:199], v[76:79]
	v_mfma_f32_16x16x32_bf16 v[68:71], v[164:167], v[206:209], v[68:71]
	v_mfma_f32_16x16x32_bf16 v[64:67], v[172:175], v[206:209], v[64:67]
	v_mfma_f32_16x16x32_bf16 v[116:119], v[168:171], v[184:187], v[116:119]
	v_mfma_f32_16x16x32_bf16 v[108:111], v[176:179], v[184:187], v[108:111]
	v_mfma_f32_16x16x32_bf16 v[100:103], v[168:171], v[192:195], v[100:103]
	v_mfma_f32_16x16x32_bf16 v[92:95], v[176:179], v[192:195], v[92:95]
	v_mfma_f32_16x16x32_bf16 v[84:87], v[168:171], v[202:205], v[84:87]
	v_mfma_f32_16x16x32_bf16 v[76:79], v[176:179], v[202:205], v[76:79]
	v_mfma_f32_16x16x32_bf16 v[68:71], v[168:171], v[210:213], v[68:71]
	v_mfma_f32_16x16x32_bf16 v[64:67], v[176:179], v[210:213], v[64:67]
	s_barrier
	s_add_i32 s79, s72, s62
	v_lshl_add_u64 v[144:145], s[54:55], 0, v[130:131]
	s_mov_b32 m0, s79
	ds_read_b128 v[180:183], v151 offset:16384
	ds_read_b128 v[184:187], v151 offset:17408
	ds_read_b128 v[188:191], v151 offset:18432
	ds_read_b128 v[192:195], v151 offset:19456
	ds_read_b128 v[196:199], v151 offset:20480
	ds_read_b128 v[202:205], v151 offset:21504
	ds_read_b128 v[206:209], v151 offset:22528
	ds_read_b128 v[210:213], v151 offset:23552
	global_load_lds_dwordx4 v[144:145], off
	s_add_i32 m0, s79, 0x2000
	s_add_u32 s80, s54, 0xb0000
	v_lshl_add_u64 v[214:215], s[54:55], 0, v[128:129]
	s_addc_u32 s81, s55, 0
	s_add_i32 s79, s73, s62
	global_load_lds_dwordx4 v[214:215], off
	v_lshl_add_u64 v[216:217], s[80:81], 0, v[130:131]
	s_mov_b32 m0, s79
	v_lshl_add_u64 v[218:219], s[58:59], 0, v[128:129]
	global_load_lds_dwordx4 v[216:217], off
	v_lshl_add_u64 v[216:217], s[80:81], 0, v[128:129]
	s_add_i32 m0, s79, 0x2000
	s_nop 0
	global_load_lds_dwordx4 v[216:217], off
	v_lshl_add_u64 v[216:217], s[58:59], 0, v[130:131]
	s_mov_b32 m0, s63
	s_nop 0
	global_load_lds_dwordx4 v[216:217], off
	s_mov_b32 m0, s64
	s_nop 0
	global_load_lds_dwordx4 v[218:219], off
	s_waitcnt vmcnt(8)
	s_waitcnt lgkmcnt(0)
	s_barrier
	s_waitcnt lgkmcnt(0)
	v_mfma_f32_16x16x32_bf16 v[60:63], v[140:143], v[180:183], v[60:63]
	v_mfma_f32_16x16x32_bf16 v[56:59], v[156:159], v[180:183], v[56:59]
	v_mfma_f32_16x16x32_bf16 v[48:51], v[140:143], v[188:191], v[48:51]
	v_mfma_f32_16x16x32_bf16 v[40:43], v[156:159], v[188:191], v[40:43]
	v_mfma_f32_16x16x32_bf16 v[32:35], v[140:143], v[196:199], v[32:35]
	v_mfma_f32_16x16x32_bf16 v[24:27], v[156:159], v[196:199], v[24:27]
	v_mfma_f32_16x16x32_bf16 v[16:19], v[140:143], v[206:209], v[16:19]
	v_mfma_f32_16x16x32_bf16 v[8:11], v[156:159], v[206:209], v[8:11]
	v_mfma_f32_16x16x32_bf16 v[60:63], v[152:155], v[184:187], v[60:63]
	v_mfma_f32_16x16x32_bf16 v[56:59], v[160:163], v[184:187], v[56:59]
	v_mfma_f32_16x16x32_bf16 v[48:51], v[152:155], v[192:195], v[48:51]
	v_mfma_f32_16x16x32_bf16 v[40:43], v[160:163], v[192:195], v[40:43]
	v_mfma_f32_16x16x32_bf16 v[32:35], v[152:155], v[202:205], v[32:35]
	v_mfma_f32_16x16x32_bf16 v[24:27], v[160:163], v[202:205], v[24:27]
	v_mfma_f32_16x16x32_bf16 v[16:19], v[152:155], v[210:213], v[16:19]
	v_mfma_f32_16x16x32_bf16 v[8:11], v[160:163], v[210:213], v[8:11]
	v_mfma_f32_16x16x32_bf16 v[52:55], v[164:167], v[180:183], v[52:55]
	v_mfma_f32_16x16x32_bf16 v[44:47], v[172:175], v[180:183], v[44:47]
	v_mfma_f32_16x16x32_bf16 v[36:39], v[164:167], v[188:191], v[36:39]
	v_mfma_f32_16x16x32_bf16 v[28:31], v[172:175], v[188:191], v[28:31]
	v_mfma_f32_16x16x32_bf16 v[20:23], v[164:167], v[196:199], v[20:23]
	v_mfma_f32_16x16x32_bf16 v[12:15], v[172:175], v[196:199], v[12:15]
	v_mfma_f32_16x16x32_bf16 v[4:7], v[164:167], v[206:209], v[4:7]
	v_mfma_f32_16x16x32_bf16 v[0:3], v[172:175], v[206:209], v[0:3]
	v_mfma_f32_16x16x32_bf16 v[52:55], v[168:171], v[184:187], v[52:55]
	v_mfma_f32_16x16x32_bf16 v[44:47], v[176:179], v[184:187], v[44:47]
	v_mfma_f32_16x16x32_bf16 v[36:39], v[168:171], v[192:195], v[36:39]
	v_mfma_f32_16x16x32_bf16 v[28:31], v[176:179], v[192:195], v[28:31]
	v_mfma_f32_16x16x32_bf16 v[20:23], v[168:171], v[202:205], v[20:23]
	v_mfma_f32_16x16x32_bf16 v[12:15], v[176:179], v[202:205], v[12:15]
	v_mfma_f32_16x16x32_bf16 v[4:7], v[168:171], v[210:213], v[4:7]
	v_mfma_f32_16x16x32_bf16 v[0:3], v[176:179], v[210:213], v[0:3]
	s_barrier
	s_add_i32 s79, 0, 0x18000
	s_add_i32 s80, 0, 0x1c000
	v_add_u32_e32 v160, s79, v147
	v_add_u32_e32 v176, s80, v147
	ds_read_b128 v[140:143], v160
	ds_read_b128 v[152:155], v160 offset:1024
	ds_read_b128 v[156:159], v160 offset:2048
	ds_read_b128 v[160:163], v160 offset:3072
	ds_read_b128 v[164:167], v176
	ds_read_b128 v[168:171], v176 offset:1024
	ds_read_b128 v[172:175], v176 offset:2048
	ds_read_b128 v[176:179], v176 offset:3072
	s_add_u32 s58, s58, 0xb0000
	s_addc_u32 s59, s59, 0
	s_mov_b32 m0, s65
	v_lshl_add_u64 v[220:221], s[58:59], 0, v[130:131]
	ds_read_b128 v[180:183], v151 offset:32768
	ds_read_b128 v[184:187], v151 offset:33792
	ds_read_b128 v[188:191], v151 offset:34816
	ds_read_b128 v[192:195], v151 offset:35840
	ds_read_b128 v[196:199], v151 offset:36864
	ds_read_b128 v[202:205], v151 offset:37888
	ds_read_b128 v[206:209], v151 offset:38912
	ds_read_b128 v[210:213], v151 offset:39936
	global_load_lds_dwordx4 v[220:221], off
	v_lshl_add_u64 v[220:221], s[58:59], 0, v[128:129]
	s_mov_b32 m0, s66
	s_nop 0
	global_load_lds_dwordx4 v[220:221], off
	s_waitcnt vmcnt(8)
	s_waitcnt lgkmcnt(0)
	s_barrier
	s_waitcnt lgkmcnt(0)
	v_mfma_f32_16x16x32_bf16 v[124:127], v[140:143], v[180:183], v[124:127]
	v_mfma_f32_16x16x32_bf16 v[120:123], v[156:159], v[180:183], v[120:123]
	v_mfma_f32_16x16x32_bf16 v[112:115], v[140:143], v[188:191], v[112:115]
	v_mfma_f32_16x16x32_bf16 v[104:107], v[156:159], v[188:191], v[104:107]
	v_mfma_f32_16x16x32_bf16 v[96:99], v[140:143], v[196:199], v[96:99]
	v_mfma_f32_16x16x32_bf16 v[88:91], v[156:159], v[196:199], v[88:91]
	v_mfma_f32_16x16x32_bf16 v[80:83], v[140:143], v[206:209], v[80:83]
	v_mfma_f32_16x16x32_bf16 v[72:75], v[156:159], v[206:209], v[72:75]
	v_mfma_f32_16x16x32_bf16 v[124:127], v[152:155], v[184:187], v[124:127]
	v_mfma_f32_16x16x32_bf16 v[120:123], v[160:163], v[184:187], v[120:123]
	v_mfma_f32_16x16x32_bf16 v[112:115], v[152:155], v[192:195], v[112:115]
	v_mfma_f32_16x16x32_bf16 v[104:107], v[160:163], v[192:195], v[104:107]
	v_mfma_f32_16x16x32_bf16 v[96:99], v[152:155], v[202:205], v[96:99]
	v_mfma_f32_16x16x32_bf16 v[88:91], v[160:163], v[202:205], v[88:91]
	v_mfma_f32_16x16x32_bf16 v[80:83], v[152:155], v[210:213], v[80:83]
	v_mfma_f32_16x16x32_bf16 v[72:75], v[160:163], v[210:213], v[72:75]
	v_mfma_f32_16x16x32_bf16 v[116:119], v[164:167], v[180:183], v[116:119]
	v_mfma_f32_16x16x32_bf16 v[108:111], v[172:175], v[180:183], v[108:111]
	v_mfma_f32_16x16x32_bf16 v[100:103], v[164:167], v[188:191], v[100:103]
	v_mfma_f32_16x16x32_bf16 v[92:95], v[172:175], v[188:191], v[92:95]
	v_mfma_f32_16x16x32_bf16 v[84:87], v[164:167], v[196:199], v[84:87]
	v_mfma_f32_16x16x32_bf16 v[76:79], v[172:175], v[196:199], v[76:79]
	v_mfma_f32_16x16x32_bf16 v[68:71], v[164:167], v[206:209], v[68:71]
	v_mfma_f32_16x16x32_bf16 v[64:67], v[172:175], v[206:209], v[64:67]
	v_mfma_f32_16x16x32_bf16 v[116:119], v[168:171], v[184:187], v[116:119]
	v_mfma_f32_16x16x32_bf16 v[108:111], v[176:179], v[184:187], v[108:111]
	v_mfma_f32_16x16x32_bf16 v[100:103], v[168:171], v[192:195], v[100:103]
	v_mfma_f32_16x16x32_bf16 v[92:95], v[176:179], v[192:195], v[92:95]
	v_mfma_f32_16x16x32_bf16 v[84:87], v[168:171], v[202:205], v[84:87]
	v_mfma_f32_16x16x32_bf16 v[76:79], v[176:179], v[202:205], v[76:79]
	v_mfma_f32_16x16x32_bf16 v[68:71], v[168:171], v[210:213], v[68:71]
	v_mfma_f32_16x16x32_bf16 v[64:67], v[176:179], v[210:213], v[64:67]
	s_barrier
	s_add_i32 s58, s79, s62
	v_lshl_add_u64 v[144:145], v[144:145], 0, s[10:11]
	s_mov_b32 m0, s58
	ds_read_b128 v[180:183], v151 offset:49152
	ds_read_b128 v[184:187], v151 offset:50176
	ds_read_b128 v[188:191], v151 offset:51200
	ds_read_b128 v[192:195], v151 offset:52224
	ds_read_b128 v[196:199], v151 offset:53248
	ds_read_b128 v[202:205], v151 offset:54272
	ds_read_b128 v[206:209], v151 offset:55296
	ds_read_b128 v[210:213], v151 offset:56320
	global_load_lds_dwordx4 v[144:145], off
	s_add_i32 m0, s58, 0x2000
	s_add_u32 s54, s54, 0xb0080
	v_lshl_add_u64 v[144:145], v[214:215], 0, s[10:11]
	s_addc_u32 s55, s55, 0
	s_add_i32 s58, s80, s62
	global_load_lds_dwordx4 v[144:145], off
	v_lshl_add_u64 v[144:145], s[54:55], 0, v[130:131]
	s_mov_b32 m0, s58
	s_nop 0
	global_load_lds_dwordx4 v[144:145], off
	v_lshl_add_u64 v[144:145], s[54:55], 0, v[128:129]
	s_add_i32 m0, s58, 0x2000
	s_nop 0
	global_load_lds_dwordx4 v[144:145], off
	v_lshl_add_u64 v[144:145], v[216:217], 0, s[10:11]
	s_mov_b32 m0, s68
	s_nop 0
	global_load_lds_dwordx4 v[144:145], off
	v_lshl_add_u64 v[144:145], v[218:219], 0, s[10:11]
	s_mov_b32 m0, s69
	s_nop 0
	global_load_lds_dwordx4 v[144:145], off
	s_waitcnt vmcnt(8)
	s_waitcnt lgkmcnt(0)
	s_barrier
	s_waitcnt lgkmcnt(0)
	v_mfma_f32_16x16x32_bf16 v[60:63], v[140:143], v[180:183], v[60:63]
	v_mfma_f32_16x16x32_bf16 v[56:59], v[156:159], v[180:183], v[56:59]
	v_mfma_f32_16x16x32_bf16 v[48:51], v[140:143], v[188:191], v[48:51]
	v_mfma_f32_16x16x32_bf16 v[40:43], v[156:159], v[188:191], v[40:43]
	v_mfma_f32_16x16x32_bf16 v[32:35], v[140:143], v[196:199], v[32:35]
	v_mfma_f32_16x16x32_bf16 v[24:27], v[156:159], v[196:199], v[24:27]
	v_mfma_f32_16x16x32_bf16 v[16:19], v[140:143], v[206:209], v[16:19]
	v_mfma_f32_16x16x32_bf16 v[8:11], v[156:159], v[206:209], v[8:11]
	v_mfma_f32_16x16x32_bf16 v[60:63], v[152:155], v[184:187], v[60:63]
	v_mfma_f32_16x16x32_bf16 v[56:59], v[160:163], v[184:187], v[56:59]
	v_mfma_f32_16x16x32_bf16 v[48:51], v[152:155], v[192:195], v[48:51]
	v_mfma_f32_16x16x32_bf16 v[40:43], v[160:163], v[192:195], v[40:43]
	v_mfma_f32_16x16x32_bf16 v[32:35], v[152:155], v[202:205], v[32:35]
	v_mfma_f32_16x16x32_bf16 v[24:27], v[160:163], v[202:205], v[24:27]
	v_mfma_f32_16x16x32_bf16 v[16:19], v[152:155], v[210:213], v[16:19]
	v_mfma_f32_16x16x32_bf16 v[8:11], v[160:163], v[210:213], v[8:11]
	v_mfma_f32_16x16x32_bf16 v[52:55], v[164:167], v[180:183], v[52:55]
	v_mfma_f32_16x16x32_bf16 v[44:47], v[172:175], v[180:183], v[44:47]
	v_mfma_f32_16x16x32_bf16 v[36:39], v[164:167], v[188:191], v[36:39]
	v_mfma_f32_16x16x32_bf16 v[28:31], v[172:175], v[188:191], v[28:31]
	v_mfma_f32_16x16x32_bf16 v[20:23], v[164:167], v[196:199], v[20:23]
	v_mfma_f32_16x16x32_bf16 v[12:15], v[172:175], v[196:199], v[12:15]
	v_mfma_f32_16x16x32_bf16 v[4:7], v[164:167], v[206:209], v[4:7]
	v_mfma_f32_16x16x32_bf16 v[0:3], v[172:175], v[206:209], v[0:3]
	v_mfma_f32_16x16x32_bf16 v[52:55], v[168:171], v[184:187], v[52:55]
	v_mfma_f32_16x16x32_bf16 v[44:47], v[176:179], v[184:187], v[44:47]
	v_mfma_f32_16x16x32_bf16 v[36:39], v[168:171], v[192:195], v[36:39]
	v_mfma_f32_16x16x32_bf16 v[28:31], v[176:179], v[192:195], v[28:31]
	v_mfma_f32_16x16x32_bf16 v[20:23], v[168:171], v[202:205], v[20:23]
	v_mfma_f32_16x16x32_bf16 v[12:15], v[176:179], v[202:205], v[12:15]
	v_mfma_f32_16x16x32_bf16 v[4:7], v[168:171], v[210:213], v[4:7]
	v_mfma_f32_16x16x32_bf16 v[0:3], v[176:179], v[210:213], v[0:3]
	s_add_i32 s78, s78, 2
	s_add_u32 s52, s52, 0x100
	s_addc_u32 s53, s53, 0
	s_add_u32 s76, s76, 0x100
	s_addc_u32 s77, s77, 0
	s_cmp_gt_u32 s78, 41
	s_barrier
	s_cbranch_scc0 .LBB0_1018
	s_setprio 0
	s_and_b64 vcc, exec, s[12:13]
	s_cbranch_vccz .LBB0_1021
	s_barrier

.Lgp_1155:
.LBB0_1155:
	ds_read_b128 v[144:147], v151
	ds_read_b128 v[154:157], v151 offset:1024
	ds_read_b128 v[158:161], v151 offset:2048
	ds_read_b128 v[162:165], v151 offset:3072
	ds_read_b128 v[166:169], v152
	ds_read_b128 v[170:173], v152 offset:1024
	ds_read_b128 v[174:177], v152 offset:2048
	ds_read_b128 v[178:181], v152 offset:3072
	s_add_u32 s44, s34, 0xfffc0080
	s_addc_u32 s45, s35, -1
	s_cmp_eq_u32 s74, 12
	s_cselect_b32 s51, s15, s45
	s_cselect_b32 s50, s70, s44
	s_cselect_b32 s45, s13, s73
	s_cselect_b32 s44, s71, s72
	v_lshl_add_u64 v[198:199], s[34:35], 0, v[136:137]
	s_add_i32 m0, s58, 0xc000
	ds_read_b128 v[182:185], v153
	ds_read_b128 v[186:189], v153 offset:1024
	ds_read_b128 v[190:193], v153 offset:2048
	ds_read_b128 v[194:197], v153 offset:3072
	ds_read_b128 v[202:205], v153 offset:4096
	ds_read_b128 v[206:209], v153 offset:5120
	ds_read_b128 v[210:213], v153 offset:6144
	ds_read_b128 v[214:217], v153 offset:7168
	global_load_lds_dwordx4 v[198:199], off
	v_lshl_add_u64 v[198:199], s[34:35], 0, v[138:139]
	s_add_i32 m0, s58, 0xe000
	s_nop 0
	global_load_lds_dwordx4 v[198:199], off
	s_waitcnt vmcnt(8)
	s_waitcnt lgkmcnt(0)
	s_barrier
	s_waitcnt lgkmcnt(0)
	v_mfma_f32_16x16x32_bf16 v[124:127], v[144:147], v[182:185], v[124:127]
	v_mfma_f32_16x16x32_bf16 v[120:123], v[158:161], v[182:185], v[120:123]
	v_mfma_f32_16x16x32_bf16 v[116:119], v[144:147], v[190:193], v[116:119]
	v_mfma_f32_16x16x32_bf16 v[108:111], v[158:161], v[190:193], v[108:111]
	v_mfma_f32_16x16x32_bf16 v[100:103], v[144:147], v[202:205], v[100:103]
	v_mfma_f32_16x16x32_bf16 v[92:95], v[158:161], v[202:205], v[92:95]
	v_mfma_f32_16x16x32_bf16 v[84:87], v[144:147], v[210:213], v[84:87]
	v_mfma_f32_16x16x32_bf16 v[76:79], v[158:161], v[210:213], v[76:79]
	v_mfma_f32_16x16x32_bf16 v[124:127], v[154:157], v[186:189], v[124:127]
	v_mfma_f32_16x16x32_bf16 v[120:123], v[162:165], v[186:189], v[120:123]
	v_mfma_f32_16x16x32_bf16 v[116:119], v[154:157], v[194:197], v[116:119]
	v_mfma_f32_16x16x32_bf16 v[108:111], v[162:165], v[194:197], v[108:111]
	v_mfma_f32_16x16x32_bf16 v[100:103], v[154:157], v[206:209], v[100:103]
	v_mfma_f32_16x16x32_bf16 v[92:95], v[162:165], v[206:209], v[92:95]
	v_mfma_f32_16x16x32_bf16 v[84:87], v[154:157], v[214:217], v[84:87]
	v_mfma_f32_16x16x32_bf16 v[76:79], v[162:165], v[214:217], v[76:79]
	v_mfma_f32_16x16x32_bf16 v[112:115], v[166:169], v[182:185], v[112:115]
	v_mfma_f32_16x16x32_bf16 v[104:107], v[174:177], v[182:185], v[104:107]
	v_mfma_f32_16x16x32_bf16 v[96:99], v[166:169], v[190:193], v[96:99]
	v_mfma_f32_16x16x32_bf16 v[88:91], v[174:177], v[190:193], v[88:91]
	v_mfma_f32_16x16x32_bf16 v[80:83], v[166:169], v[202:205], v[80:83]
	v_mfma_f32_16x16x32_bf16 v[72:75], v[174:177], v[202:205], v[72:75]
	v_mfma_f32_16x16x32_bf16 v[68:71], v[166:169], v[210:213], v[68:71]
	v_mfma_f32_16x16x32_bf16 v[64:67], v[174:177], v[210:213], v[64:67]
	v_mfma_f32_16x16x32_bf16 v[112:115], v[170:173], v[186:189], v[112:115]
	v_mfma_f32_16x16x32_bf16 v[104:107], v[178:181], v[186:189], v[104:107]
	v_mfma_f32_16x16x32_bf16 v[96:99], v[170:173], v[194:197], v[96:99]
	v_mfma_f32_16x16x32_bf16 v[88:91], v[178:181], v[194:197], v[88:91]
	v_mfma_f32_16x16x32_bf16 v[80:83], v[170:173], v[206:209], v[80:83]
	v_mfma_f32_16x16x32_bf16 v[72:75], v[178:181], v[206:209], v[72:75]
	v_mfma_f32_16x16x32_bf16 v[68:71], v[170:173], v[214:217], v[68:71]
	v_mfma_f32_16x16x32_bf16 v[64:67], v[178:181], v[214:217], v[64:67]
	s_barrier
	s_add_i32 s75, s65, s55
	v_lshl_add_u64 v[198:199], s[44:45], 0, v[132:133]
	s_mov_b32 m0, s75
	ds_read_b128 v[182:185], v153 offset:16384
	ds_read_b128 v[186:189], v153 offset:17408
	ds_read_b128 v[190:193], v153 offset:18432
	ds_read_b128 v[194:197], v153 offset:19456
	ds_read_b128 v[202:205], v153 offset:20480
	ds_read_b128 v[206:209], v153 offset:21504
	ds_read_b128 v[210:213], v153 offset:22528
	ds_read_b128 v[214:217], v153 offset:23552
	global_load_lds_dwordx4 v[198:199], off
	s_add_i32 m0, s75, 0x2000
	s_add_u32 s76, s44, 0x40000
	v_lshl_add_u64 v[218:219], s[44:45], 0, v[128:129]
	s_addc_u32 s77, s45, 0
	s_add_i32 s75, s66, s55
	global_load_lds_dwordx4 v[218:219], off
	v_lshl_add_u64 v[220:221], s[76:77], 0, v[132:133]
	s_mov_b32 m0, s75
	v_lshl_add_u64 v[222:223], s[50:51], 0, v[130:131]
	global_load_lds_dwordx4 v[220:221], off
	v_lshl_add_u64 v[220:221], s[76:77], 0, v[128:129]
	s_add_i32 m0, s75, 0x2000
	s_nop 0
	global_load_lds_dwordx4 v[220:221], off
	v_lshl_add_u64 v[220:221], s[50:51], 0, v[134:135]
	s_mov_b32 m0, s58
	s_nop 0
	global_load_lds_dwordx4 v[220:221], off
	s_mov_b32 m0, s59
	s_nop 0
	global_load_lds_dwordx4 v[222:223], off
	s_waitcnt vmcnt(8)
	s_waitcnt lgkmcnt(0)
	s_barrier
	s_waitcnt lgkmcnt(0)
	v_mfma_f32_16x16x32_bf16 v[60:63], v[144:147], v[182:185], v[60:63]
	v_mfma_f32_16x16x32_bf16 v[56:59], v[158:161], v[182:185], v[56:59]
	v_mfma_f32_16x16x32_bf16 v[52:55], v[144:147], v[190:193], v[52:55]
	v_mfma_f32_16x16x32_bf16 v[44:47], v[158:161], v[190:193], v[44:47]
	v_mfma_f32_16x16x32_bf16 v[36:39], v[144:147], v[202:205], v[36:39]
	v_mfma_f32_16x16x32_bf16 v[28:31], v[158:161], v[202:205], v[28:31]
	v_mfma_f32_16x16x32_bf16 v[20:23], v[144:147], v[210:213], v[20:23]
	v_mfma_f32_16x16x32_bf16 v[12:15], v[158:161], v[210:213], v[12:15]
	v_mfma_f32_16x16x32_bf16 v[60:63], v[154:157], v[186:189], v[60:63]
	v_mfma_f32_16x16x32_bf16 v[56:59], v[162:165], v[186:189], v[56:59]
	v_mfma_f32_16x16x32_bf16 v[52:55], v[154:157], v[194:197], v[52:55]
	v_mfma_f32_16x16x32_bf16 v[44:47], v[162:165], v[194:197], v[44:47]
	v_mfma_f32_16x16x32_bf16 v[36:39], v[154:157], v[206:209], v[36:39]
	v_mfma_f32_16x16x32_bf16 v[28:31], v[162:165], v[206:209], v[28:31]
	v_mfma_f32_16x16x32_bf16 v[20:23], v[154:157], v[214:217], v[20:23]
	v_mfma_f32_16x16x32_bf16 v[12:15], v[162:165], v[214:217], v[12:15]
	v_mfma_f32_16x16x32_bf16 v[48:51], v[166:169], v[182:185], v[48:51]
	v_mfma_f32_16x16x32_bf16 v[40:43], v[174:177], v[182:185], v[40:43]
	v_mfma_f32_16x16x32_bf16 v[32:35], v[166:169], v[190:193], v[32:35]
	v_mfma_f32_16x16x32_bf16 v[24:27], v[174:177], v[190:193], v[24:27]
	v_mfma_f32_16x16x32_bf16 v[16:19], v[166:169], v[202:205], v[16:19]
	v_mfma_f32_16x16x32_bf16 v[8:11], v[174:177], v[202:205], v[8:11]
	v_mfma_f32_16x16x32_bf16 v[4:7], v[166:169], v[210:213], v[4:7]
	v_mfma_f32_16x16x32_bf16 v[0:3], v[174:177], v[210:213], v[0:3]
	v_mfma_f32_16x16x32_bf16 v[48:51], v[170:173], v[186:189], v[48:51]
	v_mfma_f32_16x16x32_bf16 v[40:43], v[178:181], v[186:189], v[40:43]
	v_mfma_f32_16x16x32_bf16 v[32:35], v[170:173], v[194:197], v[32:35]
	v_mfma_f32_16x16x32_bf16 v[24:27], v[178:181], v[194:197], v[24:27]
	v_mfma_f32_16x16x32_bf16 v[16:19], v[170:173], v[206:209], v[16:19]
	v_mfma_f32_16x16x32_bf16 v[8:11], v[178:181], v[206:209], v[8:11]
	v_mfma_f32_16x16x32_bf16 v[4:7], v[170:173], v[214:217], v[4:7]
	v_mfma_f32_16x16x32_bf16 v[0:3], v[178:181], v[214:217], v[0:3]
	s_barrier
	s_add_i32 s75, 0, 0x18000
	s_add_i32 s76, 0, 0x1c000
	v_add_u32_e32 v162, s75, v149
	v_add_u32_e32 v178, s76, v149
	ds_read_b128 v[144:147], v162
	ds_read_b128 v[154:157], v162 offset:1024
	ds_read_b128 v[158:161], v162 offset:2048
	ds_read_b128 v[162:165], v162 offset:3072
	ds_read_b128 v[166:169], v178
	ds_read_b128 v[170:173], v178 offset:1024
	ds_read_b128 v[174:177], v178 offset:2048
	ds_read_b128 v[178:181], v178 offset:3072
	s_add_u32 s50, s50, 0x40000
	s_addc_u32 s51, s51, 0
	s_mov_b32 m0, s60
	v_lshl_add_u64 v[224:225], s[50:51], 0, v[134:135]
	ds_read_b128 v[182:185], v153 offset:32768
	ds_read_b128 v[186:189], v153 offset:33792
	ds_read_b128 v[190:193], v153 offset:34816
	ds_read_b128 v[194:197], v153 offset:35840
	ds_read_b128 v[202:205], v153 offset:36864
	ds_read_b128 v[206:209], v153 offset:37888
	ds_read_b128 v[210:213], v153 offset:38912
	ds_read_b128 v[214:217], v153 offset:39936
	global_load_lds_dwordx4 v[224:225], off
	v_lshl_add_u64 v[224:225], s[50:51], 0, v[130:131]
	s_mov_b32 m0, s61
	s_nop 0
	global_load_lds_dwordx4 v[224:225], off
	s_waitcnt vmcnt(8)
	s_waitcnt lgkmcnt(0)
	s_barrier
	s_waitcnt lgkmcnt(0)
	v_mfma_f32_16x16x32_bf16 v[124:127], v[144:147], v[182:185], v[124:127]
	v_mfma_f32_16x16x32_bf16 v[120:123], v[158:161], v[182:185], v[120:123]
	v_mfma_f32_16x16x32_bf16 v[116:119], v[144:147], v[190:193], v[116:119]
	v_mfma_f32_16x16x32_bf16 v[108:111], v[158:161], v[190:193], v[108:111]
	v_mfma_f32_16x16x32_bf16 v[100:103], v[144:147], v[202:205], v[100:103]
	v_mfma_f32_16x16x32_bf16 v[92:95], v[158:161], v[202:205], v[92:95]
	v_mfma_f32_16x16x32_bf16 v[84:87], v[144:147], v[210:213], v[84:87]
	v_mfma_f32_16x16x32_bf16 v[76:79], v[158:161], v[210:213], v[76:79]
	v_mfma_f32_16x16x32_bf16 v[124:127], v[154:157], v[186:189], v[124:127]
	v_mfma_f32_16x16x32_bf16 v[120:123], v[162:165], v[186:189], v[120:123]
	v_mfma_f32_16x16x32_bf16 v[116:119], v[154:157], v[194:197], v[116:119]
	v_mfma_f32_16x16x32_bf16 v[108:111], v[162:165], v[194:197], v[108:111]
	v_mfma_f32_16x16x32_bf16 v[100:103], v[154:157], v[206:209], v[100:103]
	v_mfma_f32_16x16x32_bf16 v[92:95], v[162:165], v[206:209], v[92:95]
	v_mfma_f32_16x16x32_bf16 v[84:87], v[154:157], v[214:217], v[84:87]
	v_mfma_f32_16x16x32_bf16 v[76:79], v[162:165], v[214:217], v[76:79]
	v_mfma_f32_16x16x32_bf16 v[112:115], v[166:169], v[182:185], v[112:115]
	v_mfma_f32_16x16x32_bf16 v[104:107], v[174:177], v[182:185], v[104:107]
	v_mfma_f32_16x16x32_bf16 v[96:99], v[166:169], v[190:193], v[96:99]
	v_mfma_f32_16x16x32_bf16 v[88:91], v[174:177], v[190:193], v[88:91]
	v_mfma_f32_16x16x32_bf16 v[80:83], v[166:169], v[202:205], v[80:83]
	v_mfma_f32_16x16x32_bf16 v[72:75], v[174:177], v[202:205], v[72:75]
	v_mfma_f32_16x16x32_bf16 v[68:71], v[166:169], v[210:213], v[68:71]
	v_mfma_f32_16x16x32_bf16 v[64:67], v[174:177], v[210:213], v[64:67]
	v_mfma_f32_16x16x32_bf16 v[112:115], v[170:173], v[186:189], v[112:115]
	v_mfma_f32_16x16x32_bf16 v[104:107], v[178:181], v[186:189], v[104:107]
	v_mfma_f32_16x16x32_bf16 v[96:99], v[170:173], v[194:197], v[96:99]
	v_mfma_f32_16x16x32_bf16 v[88:91], v[178:181], v[194:197], v[88:91]
	v_mfma_f32_16x16x32_bf16 v[80:83], v[170:173], v[206:209], v[80:83]
	v_mfma_f32_16x16x32_bf16 v[72:75], v[178:181], v[206:209], v[72:75]
	v_mfma_f32_16x16x32_bf16 v[68:71], v[170:173], v[214:217], v[68:71]
	v_mfma_f32_16x16x32_bf16 v[64:67], v[178:181], v[214:217], v[64:67]
	s_barrier
	s_add_i32 s50, s75, s55
	v_lshl_add_u64 v[198:199], v[198:199], 0, s[8:9]
	s_mov_b32 m0, s50
	ds_read_b128 v[182:185], v153 offset:49152
	ds_read_b128 v[186:189], v153 offset:50176
	ds_read_b128 v[190:193], v153 offset:51200
	ds_read_b128 v[194:197], v153 offset:52224
	ds_read_b128 v[202:205], v153 offset:53248
	ds_read_b128 v[206:209], v153 offset:54272
	ds_read_b128 v[210:213], v153 offset:55296
	ds_read_b128 v[214:217], v153 offset:56320
	global_load_lds_dwordx4 v[198:199], off
	s_add_i32 m0, s50, 0x2000
	s_add_u32 s44, s44, 0x40080
	v_lshl_add_u64 v[198:199], v[218:219], 0, s[8:9]
	s_addc_u32 s45, s45, 0
	s_add_i32 s50, s76, s55
	global_load_lds_dwordx4 v[198:199], off
	v_lshl_add_u64 v[198:199], s[44:45], 0, v[132:133]
	s_mov_b32 m0, s50
	s_nop 0
	global_load_lds_dwordx4 v[198:199], off
	v_lshl_add_u64 v[198:199], s[44:45], 0, v[128:129]
	s_add_i32 m0, s50, 0x2000
	s_nop 0
	global_load_lds_dwordx4 v[198:199], off
	v_lshl_add_u64 v[198:199], v[220:221], 0, s[8:9]
	s_mov_b32 m0, s63
	s_nop 0
	global_load_lds_dwordx4 v[198:199], off
	v_lshl_add_u64 v[198:199], v[222:223], 0, s[8:9]
	s_mov_b32 m0, s64
	s_nop 0
	global_load_lds_dwordx4 v[198:199], off
	s_waitcnt vmcnt(8)
	s_waitcnt lgkmcnt(0)
	s_barrier
	s_waitcnt lgkmcnt(0)
	v_mfma_f32_16x16x32_bf16 v[60:63], v[144:147], v[182:185], v[60:63]
	v_mfma_f32_16x16x32_bf16 v[56:59], v[158:161], v[182:185], v[56:59]
	v_mfma_f32_16x16x32_bf16 v[52:55], v[144:147], v[190:193], v[52:55]
	v_mfma_f32_16x16x32_bf16 v[44:47], v[158:161], v[190:193], v[44:47]
	v_mfma_f32_16x16x32_bf16 v[36:39], v[144:147], v[202:205], v[36:39]
	v_mfma_f32_16x16x32_bf16 v[28:31], v[158:161], v[202:205], v[28:31]
	v_mfma_f32_16x16x32_bf16 v[20:23], v[144:147], v[210:213], v[20:23]
	v_mfma_f32_16x16x32_bf16 v[12:15], v[158:161], v[210:213], v[12:15]
	v_mfma_f32_16x16x32_bf16 v[60:63], v[154:157], v[186:189], v[60:63]
	v_mfma_f32_16x16x32_bf16 v[56:59], v[162:165], v[186:189], v[56:59]
	v_mfma_f32_16x16x32_bf16 v[52:55], v[154:157], v[194:197], v[52:55]
	v_mfma_f32_16x16x32_bf16 v[44:47], v[162:165], v[194:197], v[44:47]
	v_mfma_f32_16x16x32_bf16 v[36:39], v[154:157], v[206:209], v[36:39]
	v_mfma_f32_16x16x32_bf16 v[28:31], v[162:165], v[206:209], v[28:31]
	v_mfma_f32_16x16x32_bf16 v[20:23], v[154:157], v[214:217], v[20:23]
	v_mfma_f32_16x16x32_bf16 v[12:15], v[162:165], v[214:217], v[12:15]
	v_mfma_f32_16x16x32_bf16 v[48:51], v[166:169], v[182:185], v[48:51]
	v_mfma_f32_16x16x32_bf16 v[40:43], v[174:177], v[182:185], v[40:43]
	v_mfma_f32_16x16x32_bf16 v[32:35], v[166:169], v[190:193], v[32:35]
	v_mfma_f32_16x16x32_bf16 v[24:27], v[174:177], v[190:193], v[24:27]
	v_mfma_f32_16x16x32_bf16 v[16:19], v[166:169], v[202:205], v[16:19]
	v_mfma_f32_16x16x32_bf16 v[8:11], v[174:177], v[202:205], v[8:11]
	v_mfma_f32_16x16x32_bf16 v[4:7], v[166:169], v[210:213], v[4:7]
	v_mfma_f32_16x16x32_bf16 v[0:3], v[174:177], v[210:213], v[0:3]
	v_mfma_f32_16x16x32_bf16 v[48:51], v[170:173], v[186:189], v[48:51]
	v_mfma_f32_16x16x32_bf16 v[40:43], v[178:181], v[186:189], v[40:43]
	v_mfma_f32_16x16x32_bf16 v[32:35], v[170:173], v[194:197], v[32:35]
	v_mfma_f32_16x16x32_bf16 v[24:27], v[178:181], v[194:197], v[24:27]
	v_mfma_f32_16x16x32_bf16 v[16:19], v[170:173], v[206:209], v[16:19]
	v_mfma_f32_16x16x32_bf16 v[8:11], v[178:181], v[206:209], v[8:11]
	v_mfma_f32_16x16x32_bf16 v[4:7], v[170:173], v[214:217], v[4:7]
	v_mfma_f32_16x16x32_bf16 v[0:3], v[178:181], v[214:217], v[0:3]
	s_add_i32 s74, s74, 2
	s_add_u32 s34, s34, 0x100
	s_addc_u32 s35, s35, 0
	s_add_u32 s72, s72, 0x100
	s_addc_u32 s73, s73, 0
	s_cmp_gt_u32 s74, 13
	s_barrier
	s_cbranch_scc0 .LBB0_1155
	s_setprio 0
	s_and_b64 vcc, exec, s[10:11]
	s_cbranch_vccz .LBB0_1158
	s_barrier

.Lgp_1415:
.LBB0_1415:
	ds_read_b128 v[140:143], v149
	ds_read_b128 v[152:155], v149 offset:1024
	ds_read_b128 v[156:159], v149 offset:2048
	ds_read_b128 v[160:163], v149 offset:3072
	ds_read_b128 v[164:167], v150
	ds_read_b128 v[168:171], v150 offset:1024
	ds_read_b128 v[172:175], v150 offset:2048
	ds_read_b128 v[176:179], v150 offset:3072
	s_add_u32 s58, s56, 0xfffc0080
	s_addc_u32 s59, s57, -1
	s_cmp_eq_u32 s80, 12
	s_cselect_b32 s61, s51, s59
	s_cselect_b32 s60, s76, s58
	s_cselect_b32 s59, s45, s79
	s_cselect_b32 s58, s77, s78
	v_lshl_add_u64 v[144:145], s[56:57], 0, v[132:133]
	s_add_i32 m0, s65, 0xc000
	ds_read_b128 v[180:183], v151
	ds_read_b128 v[184:187], v151 offset:1024
	ds_read_b128 v[188:191], v151 offset:2048
	ds_read_b128 v[192:195], v151 offset:3072
	ds_read_b128 v[196:199], v151 offset:4096
	ds_read_b128 v[202:205], v151 offset:5120
	ds_read_b128 v[206:209], v151 offset:6144
	ds_read_b128 v[210:213], v151 offset:7168
	global_load_lds_dwordx4 v[144:145], off
	v_lshl_add_u64 v[144:145], s[56:57], 0, v[134:135]
	s_add_i32 m0, s65, 0xe000
	s_nop 0
	global_load_lds_dwordx4 v[144:145], off
	s_waitcnt vmcnt(8)
	s_waitcnt lgkmcnt(0)
	s_barrier
	s_waitcnt lgkmcnt(0)
	v_mfma_f32_16x16x32_bf16 v[124:127], v[140:143], v[180:183], v[124:127]
	v_mfma_f32_16x16x32_bf16 v[120:123], v[156:159], v[180:183], v[120:123]
	v_mfma_f32_16x16x32_bf16 v[112:115], v[140:143], v[188:191], v[112:115]
	v_mfma_f32_16x16x32_bf16 v[104:107], v[156:159], v[188:191], v[104:107]
	v_mfma_f32_16x16x32_bf16 v[96:99], v[140:143], v[196:199], v[96:99]
	v_mfma_f32_16x16x32_bf16 v[88:91], v[156:159], v[196:199], v[88:91]
	v_mfma_f32_16x16x32_bf16 v[80:83], v[140:143], v[206:209], v[80:83]
	v_mfma_f32_16x16x32_bf16 v[72:75], v[156:159], v[206:209], v[72:75]
	v_mfma_f32_16x16x32_bf16 v[124:127], v[152:155], v[184:187], v[124:127]
	v_mfma_f32_16x16x32_bf16 v[120:123], v[160:163], v[184:187], v[120:123]
	v_mfma_f32_16x16x32_bf16 v[112:115], v[152:155], v[192:195], v[112:115]
	v_mfma_f32_16x16x32_bf16 v[104:107], v[160:163], v[192:195], v[104:107]
	v_mfma_f32_16x16x32_bf16 v[96:99], v[152:155], v[202:205], v[96:99]
	v_mfma_f32_16x16x32_bf16 v[88:91], v[160:163], v[202:205], v[88:91]
	v_mfma_f32_16x16x32_bf16 v[80:83], v[152:155], v[210:213], v[80:83]
	v_mfma_f32_16x16x32_bf16 v[72:75], v[160:163], v[210:213], v[72:75]
	v_mfma_f32_16x16x32_bf16 v[116:119], v[164:167], v[180:183], v[116:119]
	v_mfma_f32_16x16x32_bf16 v[108:111], v[172:175], v[180:183], v[108:111]
	v_mfma_f32_16x16x32_bf16 v[100:103], v[164:167], v[188:191], v[100:103]
	v_mfma_f32_16x16x32_bf16 v[92:95], v[172:175], v[188:191], v[92:95]
	v_mfma_f32_16x16x32_bf16 v[84:87], v[164:167], v[196:199], v[84:87]
	v_mfma_f32_16x16x32_bf16 v[76:79], v[172:175], v[196:199], v[76:79]
	v_mfma_f32_16x16x32_bf16 v[68:71], v[164:167], v[206:209], v[68:71]
	v_mfma_f32_16x16x32_bf16 v[64:67], v[172:175], v[206:209], v[64:67]
	v_mfma_f32_16x16x32_bf16 v[116:119], v[168:171], v[184:187], v[116:119]
	v_mfma_f32_16x16x32_bf16 v[108:111], v[176:179], v[184:187], v[108:111]
	v_mfma_f32_16x16x32_bf16 v[100:103], v[168:171], v[192:195], v[100:103]
	v_mfma_f32_16x16x32_bf16 v[92:95], v[176:179], v[192:195], v[92:95]
	v_mfma_f32_16x16x32_bf16 v[84:87], v[168:171], v[202:205], v[84:87]
	v_mfma_f32_16x16x32_bf16 v[76:79], v[176:179], v[202:205], v[76:79]
	v_mfma_f32_16x16x32_bf16 v[68:71], v[168:171], v[210:213], v[68:71]
	v_mfma_f32_16x16x32_bf16 v[64:67], v[176:179], v[210:213], v[64:67]
	s_barrier
	s_add_i32 s81, s74, s64
	v_lshl_add_u64 v[144:145], s[58:59], 0, v[130:131]
	s_mov_b32 m0, s81
	ds_read_b128 v[180:183], v151 offset:16384
	ds_read_b128 v[184:187], v151 offset:17408
	ds_read_b128 v[188:191], v151 offset:18432
	ds_read_b128 v[192:195], v151 offset:19456
	ds_read_b128 v[196:199], v151 offset:20480
	ds_read_b128 v[202:205], v151 offset:21504
	ds_read_b128 v[206:209], v151 offset:22528
	ds_read_b128 v[210:213], v151 offset:23552
	global_load_lds_dwordx4 v[144:145], off
	s_add_i32 m0, s81, 0x2000
	s_add_u32 s82, s58, 0x40000
	v_lshl_add_u64 v[214:215], s[58:59], 0, v[128:129]
	s_addc_u32 s83, s59, 0
	s_add_i32 s81, s75, s64
	global_load_lds_dwordx4 v[214:215], off
	v_lshl_add_u64 v[216:217], s[82:83], 0, v[130:131]
	s_mov_b32 m0, s81
	v_lshl_add_u64 v[218:219], s[60:61], 0, v[128:129]
	global_load_lds_dwordx4 v[216:217], off
	v_lshl_add_u64 v[216:217], s[82:83], 0, v[128:129]
	s_add_i32 m0, s81, 0x2000
	s_nop 0
	global_load_lds_dwordx4 v[216:217], off
	v_lshl_add_u64 v[216:217], s[60:61], 0, v[130:131]
	s_mov_b32 m0, s65
	s_nop 0
	global_load_lds_dwordx4 v[216:217], off
	s_mov_b32 m0, s66
	s_nop 0
	global_load_lds_dwordx4 v[218:219], off
	s_waitcnt vmcnt(8)
	s_waitcnt lgkmcnt(0)
	s_barrier
	s_waitcnt lgkmcnt(0)
	v_mfma_f32_16x16x32_bf16 v[60:63], v[140:143], v[180:183], v[60:63]
	v_mfma_f32_16x16x32_bf16 v[56:59], v[156:159], v[180:183], v[56:59]
	v_mfma_f32_16x16x32_bf16 v[48:51], v[140:143], v[188:191], v[48:51]
	v_mfma_f32_16x16x32_bf16 v[40:43], v[156:159], v[188:191], v[40:43]
	v_mfma_f32_16x16x32_bf16 v[32:35], v[140:143], v[196:199], v[32:35]
	v_mfma_f32_16x16x32_bf16 v[24:27], v[156:159], v[196:199], v[24:27]
	v_mfma_f32_16x16x32_bf16 v[16:19], v[140:143], v[206:209], v[16:19]
	v_mfma_f32_16x16x32_bf16 v[8:11], v[156:159], v[206:209], v[8:11]
	v_mfma_f32_16x16x32_bf16 v[60:63], v[152:155], v[184:187], v[60:63]
	v_mfma_f32_16x16x32_bf16 v[56:59], v[160:163], v[184:187], v[56:59]
	v_mfma_f32_16x16x32_bf16 v[48:51], v[152:155], v[192:195], v[48:51]
	v_mfma_f32_16x16x32_bf16 v[40:43], v[160:163], v[192:195], v[40:43]
	v_mfma_f32_16x16x32_bf16 v[32:35], v[152:155], v[202:205], v[32:35]
	v_mfma_f32_16x16x32_bf16 v[24:27], v[160:163], v[202:205], v[24:27]
	v_mfma_f32_16x16x32_bf16 v[16:19], v[152:155], v[210:213], v[16:19]
	v_mfma_f32_16x16x32_bf16 v[8:11], v[160:163], v[210:213], v[8:11]
	v_mfma_f32_16x16x32_bf16 v[52:55], v[164:167], v[180:183], v[52:55]
	v_mfma_f32_16x16x32_bf16 v[44:47], v[172:175], v[180:183], v[44:47]
	v_mfma_f32_16x16x32_bf16 v[36:39], v[164:167], v[188:191], v[36:39]
	v_mfma_f32_16x16x32_bf16 v[28:31], v[172:175], v[188:191], v[28:31]
	v_mfma_f32_16x16x32_bf16 v[20:23], v[164:167], v[196:199], v[20:23]
	v_mfma_f32_16x16x32_bf16 v[12:15], v[172:175], v[196:199], v[12:15]
	v_mfma_f32_16x16x32_bf16 v[4:7], v[164:167], v[206:209], v[4:7]
	v_mfma_f32_16x16x32_bf16 v[0:3], v[172:175], v[206:209], v[0:3]
	v_mfma_f32_16x16x32_bf16 v[52:55], v[168:171], v[184:187], v[52:55]
	v_mfma_f32_16x16x32_bf16 v[44:47], v[176:179], v[184:187], v[44:47]
	v_mfma_f32_16x16x32_bf16 v[36:39], v[168:171], v[192:195], v[36:39]
	v_mfma_f32_16x16x32_bf16 v[28:31], v[176:179], v[192:195], v[28:31]
	v_mfma_f32_16x16x32_bf16 v[20:23], v[168:171], v[202:205], v[20:23]
	v_mfma_f32_16x16x32_bf16 v[12:15], v[176:179], v[202:205], v[12:15]
	v_mfma_f32_16x16x32_bf16 v[4:7], v[168:171], v[210:213], v[4:7]
	v_mfma_f32_16x16x32_bf16 v[0:3], v[176:179], v[210:213], v[0:3]
	s_barrier
	s_add_i32 s81, 0, 0x18000
	s_add_i32 s82, 0, 0x1c000
	v_add_u32_e32 v160, s81, v147
	v_add_u32_e32 v176, s82, v147
	ds_read_b128 v[140:143], v160
	ds_read_b128 v[152:155], v160 offset:1024
	ds_read_b128 v[156:159], v160 offset:2048
	ds_read_b128 v[160:163], v160 offset:3072
	ds_read_b128 v[164:167], v176
	ds_read_b128 v[168:171], v176 offset:1024
	ds_read_b128 v[172:175], v176 offset:2048
	ds_read_b128 v[176:179], v176 offset:3072
	s_add_u32 s60, s60, 0x40000
	s_addc_u32 s61, s61, 0
	s_mov_b32 m0, s67
	v_lshl_add_u64 v[220:221], s[60:61], 0, v[130:131]
	ds_read_b128 v[180:183], v151 offset:32768
	ds_read_b128 v[184:187], v151 offset:33792
	ds_read_b128 v[188:191], v151 offset:34816
	ds_read_b128 v[192:195], v151 offset:35840
	ds_read_b128 v[196:199], v151 offset:36864
	ds_read_b128 v[202:205], v151 offset:37888
	ds_read_b128 v[206:209], v151 offset:38912
	ds_read_b128 v[210:213], v151 offset:39936
	global_load_lds_dwordx4 v[220:221], off
	v_lshl_add_u64 v[220:221], s[60:61], 0, v[128:129]
	s_mov_b32 m0, s68
	s_nop 0
	global_load_lds_dwordx4 v[220:221], off
	s_waitcnt vmcnt(8)
	s_waitcnt lgkmcnt(0)
	s_barrier
	s_waitcnt lgkmcnt(0)
	v_mfma_f32_16x16x32_bf16 v[124:127], v[140:143], v[180:183], v[124:127]
	v_mfma_f32_16x16x32_bf16 v[120:123], v[156:159], v[180:183], v[120:123]
	v_mfma_f32_16x16x32_bf16 v[112:115], v[140:143], v[188:191], v[112:115]
	v_mfma_f32_16x16x32_bf16 v[104:107], v[156:159], v[188:191], v[104:107]
	v_mfma_f32_16x16x32_bf16 v[96:99], v[140:143], v[196:199], v[96:99]
	v_mfma_f32_16x16x32_bf16 v[88:91], v[156:159], v[196:199], v[88:91]
	v_mfma_f32_16x16x32_bf16 v[80:83], v[140:143], v[206:209], v[80:83]
	v_mfma_f32_16x16x32_bf16 v[72:75], v[156:159], v[206:209], v[72:75]
	v_mfma_f32_16x16x32_bf16 v[124:127], v[152:155], v[184:187], v[124:127]
	v_mfma_f32_16x16x32_bf16 v[120:123], v[160:163], v[184:187], v[120:123]
	v_mfma_f32_16x16x32_bf16 v[112:115], v[152:155], v[192:195], v[112:115]
	v_mfma_f32_16x16x32_bf16 v[104:107], v[160:163], v[192:195], v[104:107]
	v_mfma_f32_16x16x32_bf16 v[96:99], v[152:155], v[202:205], v[96:99]
	v_mfma_f32_16x16x32_bf16 v[88:91], v[160:163], v[202:205], v[88:91]
	v_mfma_f32_16x16x32_bf16 v[80:83], v[152:155], v[210:213], v[80:83]
	v_mfma_f32_16x16x32_bf16 v[72:75], v[160:163], v[210:213], v[72:75]
	v_mfma_f32_16x16x32_bf16 v[116:119], v[164:167], v[180:183], v[116:119]
	v_mfma_f32_16x16x32_bf16 v[108:111], v[172:175], v[180:183], v[108:111]
	v_mfma_f32_16x16x32_bf16 v[100:103], v[164:167], v[188:191], v[100:103]
	v_mfma_f32_16x16x32_bf16 v[92:95], v[172:175], v[188:191], v[92:95]
	v_mfma_f32_16x16x32_bf16 v[84:87], v[164:167], v[196:199], v[84:87]
	v_mfma_f32_16x16x32_bf16 v[76:79], v[172:175], v[196:199], v[76:79]
	v_mfma_f32_16x16x32_bf16 v[68:71], v[164:167], v[206:209], v[68:71]
	v_mfma_f32_16x16x32_bf16 v[64:67], v[172:175], v[206:209], v[64:67]
	v_mfma_f32_16x16x32_bf16 v[116:119], v[168:171], v[184:187], v[116:119]
	v_mfma_f32_16x16x32_bf16 v[108:111], v[176:179], v[184:187], v[108:111]
	v_mfma_f32_16x16x32_bf16 v[100:103], v[168:171], v[192:195], v[100:103]
	v_mfma_f32_16x16x32_bf16 v[92:95], v[176:179], v[192:195], v[92:95]
	v_mfma_f32_16x16x32_bf16 v[84:87], v[168:171], v[202:205], v[84:87]
	v_mfma_f32_16x16x32_bf16 v[76:79], v[176:179], v[202:205], v[76:79]
	v_mfma_f32_16x16x32_bf16 v[68:71], v[168:171], v[210:213], v[68:71]
	v_mfma_f32_16x16x32_bf16 v[64:67], v[176:179], v[210:213], v[64:67]
	s_barrier
	s_add_i32 s60, s81, s64
	v_lshl_add_u64 v[144:145], v[144:145], 0, s[8:9]
	s_mov_b32 m0, s60
	ds_read_b128 v[180:183], v151 offset:49152
	ds_read_b128 v[184:187], v151 offset:50176
	ds_read_b128 v[188:191], v151 offset:51200
	ds_read_b128 v[192:195], v151 offset:52224
	ds_read_b128 v[196:199], v151 offset:53248
	ds_read_b128 v[202:205], v151 offset:54272
	ds_read_b128 v[206:209], v151 offset:55296
	ds_read_b128 v[210:213], v151 offset:56320
	global_load_lds_dwordx4 v[144:145], off
	s_add_i32 m0, s60, 0x2000
	s_add_u32 s58, s58, 0x40080
	v_lshl_add_u64 v[144:145], v[214:215], 0, s[8:9]
	s_addc_u32 s59, s59, 0
	s_add_i32 s60, s82, s64
	global_load_lds_dwordx4 v[144:145], off
	v_lshl_add_u64 v[144:145], s[58:59], 0, v[130:131]
	s_mov_b32 m0, s60
	s_nop 0
	global_load_lds_dwordx4 v[144:145], off
	v_lshl_add_u64 v[144:145], s[58:59], 0, v[128:129]
	s_add_i32 m0, s60, 0x2000
	s_nop 0
	global_load_lds_dwordx4 v[144:145], off
	v_lshl_add_u64 v[144:145], v[216:217], 0, s[8:9]
	s_mov_b32 m0, s70
	s_nop 0
	global_load_lds_dwordx4 v[144:145], off
	v_lshl_add_u64 v[144:145], v[218:219], 0, s[8:9]
	s_mov_b32 m0, s71
	s_nop 0
	global_load_lds_dwordx4 v[144:145], off
	s_waitcnt vmcnt(8)
	s_waitcnt lgkmcnt(0)
	s_barrier
	s_waitcnt lgkmcnt(0)
	v_mfma_f32_16x16x32_bf16 v[60:63], v[140:143], v[180:183], v[60:63]
	v_mfma_f32_16x16x32_bf16 v[56:59], v[156:159], v[180:183], v[56:59]
	v_mfma_f32_16x16x32_bf16 v[48:51], v[140:143], v[188:191], v[48:51]
	v_mfma_f32_16x16x32_bf16 v[40:43], v[156:159], v[188:191], v[40:43]
	v_mfma_f32_16x16x32_bf16 v[32:35], v[140:143], v[196:199], v[32:35]
	v_mfma_f32_16x16x32_bf16 v[24:27], v[156:159], v[196:199], v[24:27]
	v_mfma_f32_16x16x32_bf16 v[16:19], v[140:143], v[206:209], v[16:19]
	v_mfma_f32_16x16x32_bf16 v[8:11], v[156:159], v[206:209], v[8:11]
	v_mfma_f32_16x16x32_bf16 v[60:63], v[152:155], v[184:187], v[60:63]
	v_mfma_f32_16x16x32_bf16 v[56:59], v[160:163], v[184:187], v[56:59]
	v_mfma_f32_16x16x32_bf16 v[48:51], v[152:155], v[192:195], v[48:51]
	v_mfma_f32_16x16x32_bf16 v[40:43], v[160:163], v[192:195], v[40:43]
	v_mfma_f32_16x16x32_bf16 v[32:35], v[152:155], v[202:205], v[32:35]
	v_mfma_f32_16x16x32_bf16 v[24:27], v[160:163], v[202:205], v[24:27]
	v_mfma_f32_16x16x32_bf16 v[16:19], v[152:155], v[210:213], v[16:19]
	v_mfma_f32_16x16x32_bf16 v[8:11], v[160:163], v[210:213], v[8:11]
	v_mfma_f32_16x16x32_bf16 v[52:55], v[164:167], v[180:183], v[52:55]
	v_mfma_f32_16x16x32_bf16 v[44:47], v[172:175], v[180:183], v[44:47]
	v_mfma_f32_16x16x32_bf16 v[36:39], v[164:167], v[188:191], v[36:39]
	v_mfma_f32_16x16x32_bf16 v[28:31], v[172:175], v[188:191], v[28:31]
	v_mfma_f32_16x16x32_bf16 v[20:23], v[164:167], v[196:199], v[20:23]
	v_mfma_f32_16x16x32_bf16 v[12:15], v[172:175], v[196:199], v[12:15]
	v_mfma_f32_16x16x32_bf16 v[4:7], v[164:167], v[206:209], v[4:7]
	v_mfma_f32_16x16x32_bf16 v[0:3], v[172:175], v[206:209], v[0:3]
	v_mfma_f32_16x16x32_bf16 v[52:55], v[168:171], v[184:187], v[52:55]
	v_mfma_f32_16x16x32_bf16 v[44:47], v[176:179], v[184:187], v[44:47]
	v_mfma_f32_16x16x32_bf16 v[36:39], v[168:171], v[192:195], v[36:39]
	v_mfma_f32_16x16x32_bf16 v[28:31], v[176:179], v[192:195], v[28:31]
	v_mfma_f32_16x16x32_bf16 v[20:23], v[168:171], v[202:205], v[20:23]
	v_mfma_f32_16x16x32_bf16 v[12:15], v[176:179], v[202:205], v[12:15]
	v_mfma_f32_16x16x32_bf16 v[4:7], v[168:171], v[210:213], v[4:7]
	v_mfma_f32_16x16x32_bf16 v[0:3], v[176:179], v[210:213], v[0:3]
	s_add_i32 s80, s80, 2
	s_add_u32 s56, s56, 0x100
	s_addc_u32 s57, s57, 0
	s_add_u32 s78, s78, 0x100
	s_addc_u32 s79, s79, 0
	s_cmp_gt_u32 s80, 13
	s_barrier
	s_cbranch_scc0 .LBB0_1415
	s_setprio 0
	s_and_b64 vcc, exec, s[10:11]
	s_cbranch_vccz .LBB0_1418
	s_barrier

.Lgp_1552:
.LBB0_1552:
	ds_read_b128 v[64:67], v203
	ds_read_b128 v[68:71], v203 offset:1024
	ds_read_b128 v[72:75], v203 offset:2048
	ds_read_b128 v[76:79], v203 offset:3072
	ds_read_b128 v[80:83], v204
	ds_read_b128 v[84:87], v204 offset:1024
	ds_read_b128 v[88:91], v204 offset:2048
	ds_read_b128 v[92:95], v204 offset:3072
	s_add_u32 s62, s60, 0xfffc0080
	s_addc_u32 s63, s61, -1
	s_cmp_eq_u32 s88, 12
	s_cselect_b32 s65, s55, s63
	s_cselect_b32 s64, s84, s62
	s_cselect_b32 s63, s53, s87
	s_cselect_b32 s62, s85, s86
	v_lshl_add_u64 v[220:221], s[60:61], 0, v[172:173]
	s_add_i32 m0, s71, 0xc000
	ds_read_b128 v[180:183], v205
	ds_read_b128 v[184:187], v205 offset:1024
	ds_read_b128 v[188:191], v205 offset:2048
	ds_read_b128 v[192:195], v205 offset:3072
	ds_read_b128 v[196:199], v205 offset:4096
	ds_read_b128 v[208:211], v205 offset:5120
	ds_read_b128 v[212:215], v205 offset:6144
	ds_read_b128 v[216:219], v205 offset:7168
	global_load_lds_dwordx4 v[220:221], off
	v_lshl_add_u64 v[220:221], s[60:61], 0, v[174:175]
	s_add_i32 m0, s71, 0xe000
	s_nop 0
	global_load_lds_dwordx4 v[220:221], off
	s_waitcnt vmcnt(8)
	s_waitcnt lgkmcnt(0)
	s_barrier
	s_waitcnt lgkmcnt(0)
	v_mfma_f32_16x16x32_bf16 v[148:151], v[64:67], v[180:183], v[148:151]
	v_mfma_f32_16x16x32_bf16 v[144:147], v[72:75], v[180:183], v[144:147]
	v_mfma_f32_16x16x32_bf16 v[132:135], v[64:67], v[188:191], v[132:135]
	v_mfma_f32_16x16x32_bf16 v[128:131], v[72:75], v[188:191], v[128:131]
	v_mfma_f32_16x16x32_bf16 v[116:119], v[64:67], v[196:199], v[116:119]
	v_mfma_f32_16x16x32_bf16 v[112:115], v[72:75], v[196:199], v[112:115]
	v_mfma_f32_16x16x32_bf16 v[104:107], v[64:67], v[212:215], v[104:107]
	v_mfma_f32_16x16x32_bf16 v[100:103], v[72:75], v[212:215], v[100:103]
	v_mfma_f32_16x16x32_bf16 v[148:151], v[68:71], v[184:187], v[148:151]
	v_mfma_f32_16x16x32_bf16 v[144:147], v[76:79], v[184:187], v[144:147]
	v_mfma_f32_16x16x32_bf16 v[132:135], v[68:71], v[192:195], v[132:135]
	v_mfma_f32_16x16x32_bf16 v[128:131], v[76:79], v[192:195], v[128:131]
	v_mfma_f32_16x16x32_bf16 v[116:119], v[68:71], v[208:211], v[116:119]
	v_mfma_f32_16x16x32_bf16 v[112:115], v[76:79], v[208:211], v[112:115]
	v_mfma_f32_16x16x32_bf16 v[104:107], v[68:71], v[216:219], v[104:107]
	v_mfma_f32_16x16x32_bf16 v[100:103], v[76:79], v[216:219], v[100:103]
	v_mfma_f32_16x16x32_bf16 v[152:155], v[80:83], v[180:183], v[152:155]
	v_mfma_f32_16x16x32_bf16 v[156:159], v[88:91], v[180:183], v[156:159]
	v_mfma_f32_16x16x32_bf16 v[136:139], v[80:83], v[188:191], v[136:139]
	v_mfma_f32_16x16x32_bf16 v[140:143], v[88:91], v[188:191], v[140:143]
	v_mfma_f32_16x16x32_bf16 v[120:123], v[80:83], v[196:199], v[120:123]
	v_mfma_f32_16x16x32_bf16 v[124:127], v[88:91], v[196:199], v[124:127]
	v_mfma_f32_16x16x32_bf16 v[96:99], v[80:83], v[212:215], v[96:99]
	v_mfma_f32_16x16x32_bf16 v[108:111], v[88:91], v[212:215], v[108:111]
	v_mfma_f32_16x16x32_bf16 v[152:155], v[84:87], v[184:187], v[152:155]
	v_mfma_f32_16x16x32_bf16 v[156:159], v[92:95], v[184:187], v[156:159]
	v_mfma_f32_16x16x32_bf16 v[136:139], v[84:87], v[192:195], v[136:139]
	v_mfma_f32_16x16x32_bf16 v[140:143], v[92:95], v[192:195], v[140:143]
	v_mfma_f32_16x16x32_bf16 v[120:123], v[84:87], v[208:211], v[120:123]
	v_mfma_f32_16x16x32_bf16 v[124:127], v[92:95], v[208:211], v[124:127]
	v_mfma_f32_16x16x32_bf16 v[96:99], v[84:87], v[216:219], v[96:99]
	v_mfma_f32_16x16x32_bf16 v[108:111], v[92:95], v[216:219], v[108:111]
	s_barrier
	s_add_i32 s89, s80, s70
	v_lshl_add_u64 v[220:221], s[62:63], 0, v[164:165]
	s_mov_b32 m0, s89
	ds_read_b128 v[180:183], v205 offset:16384
	ds_read_b128 v[184:187], v205 offset:17408
	ds_read_b128 v[188:191], v205 offset:18432
	ds_read_b128 v[192:195], v205 offset:19456
	ds_read_b128 v[196:199], v205 offset:20480
	ds_read_b128 v[208:211], v205 offset:21504
	ds_read_b128 v[212:215], v205 offset:22528
	ds_read_b128 v[216:219], v205 offset:23552
	global_load_lds_dwordx4 v[220:221], off
	s_add_i32 m0, s89, 0x2000
	s_add_u32 s90, s62, 0x40000
	v_lshl_add_u64 v[222:223], s[62:63], 0, v[160:161]
	s_addc_u32 s91, s63, 0
	s_add_i32 s89, s81, s70
	global_load_lds_dwordx4 v[222:223], off
	v_lshl_add_u64 v[224:225], s[90:91], 0, v[164:165]
	s_mov_b32 m0, s89
	v_lshl_add_u64 v[226:227], s[64:65], 0, v[162:163]
	global_load_lds_dwordx4 v[224:225], off
	v_lshl_add_u64 v[224:225], s[90:91], 0, v[160:161]
	s_add_i32 m0, s89, 0x2000
	s_nop 0
	global_load_lds_dwordx4 v[224:225], off
	v_lshl_add_u64 v[224:225], s[64:65], 0, v[166:167]
	s_mov_b32 m0, s71
	s_nop 0
	global_load_lds_dwordx4 v[224:225], off
	s_mov_b32 m0, s72
	s_nop 0
	global_load_lds_dwordx4 v[226:227], off
	s_waitcnt vmcnt(8)
	s_waitcnt lgkmcnt(0)
	s_barrier
	s_waitcnt lgkmcnt(0)
	v_mfma_f32_16x16x32_bf16 v[52:55], v[64:67], v[180:183], v[52:55]
	v_mfma_f32_16x16x32_bf16 v[48:51], v[72:75], v[180:183], v[48:51]
	v_mfma_f32_16x16x32_bf16 v[36:39], v[64:67], v[188:191], v[36:39]
	v_mfma_f32_16x16x32_bf16 v[32:35], v[72:75], v[188:191], v[32:35]
	v_mfma_f32_16x16x32_bf16 v[20:23], v[64:67], v[196:199], v[20:23]
	v_mfma_f32_16x16x32_bf16 v[16:19], v[72:75], v[196:199], v[16:19]
	v_mfma_f32_16x16x32_bf16 v[8:11], v[64:67], v[212:215], v[8:11]
	v_mfma_f32_16x16x32_bf16 v[4:7], v[72:75], v[212:215], v[4:7]
	v_mfma_f32_16x16x32_bf16 v[52:55], v[68:71], v[184:187], v[52:55]
	v_mfma_f32_16x16x32_bf16 v[48:51], v[76:79], v[184:187], v[48:51]
	v_mfma_f32_16x16x32_bf16 v[36:39], v[68:71], v[192:195], v[36:39]
	v_mfma_f32_16x16x32_bf16 v[32:35], v[76:79], v[192:195], v[32:35]
	v_mfma_f32_16x16x32_bf16 v[20:23], v[68:71], v[208:211], v[20:23]
	v_mfma_f32_16x16x32_bf16 v[16:19], v[76:79], v[208:211], v[16:19]
	v_mfma_f32_16x16x32_bf16 v[8:11], v[68:71], v[216:219], v[8:11]
	v_mfma_f32_16x16x32_bf16 v[4:7], v[76:79], v[216:219], v[4:7]
	v_mfma_f32_16x16x32_bf16 v[56:59], v[80:83], v[180:183], v[56:59]
	v_mfma_f32_16x16x32_bf16 v[60:63], v[88:91], v[180:183], v[60:63]
	v_mfma_f32_16x16x32_bf16 v[40:43], v[80:83], v[188:191], v[40:43]
	v_mfma_f32_16x16x32_bf16 v[44:47], v[88:91], v[188:191], v[44:47]
	v_mfma_f32_16x16x32_bf16 v[24:27], v[80:83], v[196:199], v[24:27]
	v_mfma_f32_16x16x32_bf16 v[28:31], v[88:91], v[196:199], v[28:31]
	v_mfma_f32_16x16x32_bf16 v[0:3], v[80:83], v[212:215], v[0:3]
	v_mfma_f32_16x16x32_bf16 v[12:15], v[88:91], v[212:215], v[12:15]
	v_mfma_f32_16x16x32_bf16 v[56:59], v[84:87], v[184:187], v[56:59]
	v_mfma_f32_16x16x32_bf16 v[60:63], v[92:95], v[184:187], v[60:63]
	v_mfma_f32_16x16x32_bf16 v[40:43], v[84:87], v[192:195], v[40:43]
	v_mfma_f32_16x16x32_bf16 v[44:47], v[92:95], v[192:195], v[44:47]
	v_mfma_f32_16x16x32_bf16 v[24:27], v[84:87], v[208:211], v[24:27]
	v_mfma_f32_16x16x32_bf16 v[28:31], v[92:95], v[208:211], v[28:31]
	v_mfma_f32_16x16x32_bf16 v[0:3], v[84:87], v[216:219], v[0:3]
	v_mfma_f32_16x16x32_bf16 v[12:15], v[92:95], v[216:219], v[12:15]
	s_barrier
	s_add_i32 s89, 0, 0x18000
	s_add_i32 s90, 0, 0x1c000
	v_add_u32_e32 v76, s89, v201
	v_add_u32_e32 v92, s90, v201
	ds_read_b128 v[64:67], v76
	ds_read_b128 v[68:71], v76 offset:1024
	ds_read_b128 v[72:75], v76 offset:2048
	ds_read_b128 v[76:79], v76 offset:3072
	ds_read_b128 v[80:83], v92
	ds_read_b128 v[84:87], v92 offset:1024
	ds_read_b128 v[88:91], v92 offset:2048
	ds_read_b128 v[92:95], v92 offset:3072
	s_add_u32 s64, s64, 0x40000
	s_addc_u32 s65, s65, 0
	s_mov_b32 m0, s73
	v_lshl_add_u64 v[228:229], s[64:65], 0, v[166:167]
	ds_read_b128 v[180:183], v205 offset:32768
	ds_read_b128 v[184:187], v205 offset:33792
	ds_read_b128 v[188:191], v205 offset:34816
	ds_read_b128 v[192:195], v205 offset:35840
	ds_read_b128 v[196:199], v205 offset:36864
	ds_read_b128 v[208:211], v205 offset:37888
	ds_read_b128 v[212:215], v205 offset:38912
	ds_read_b128 v[216:219], v205 offset:39936
	global_load_lds_dwordx4 v[228:229], off
	v_lshl_add_u64 v[228:229], s[64:65], 0, v[162:163]
	s_mov_b32 m0, s74
	s_nop 0
	global_load_lds_dwordx4 v[228:229], off
	s_waitcnt vmcnt(8)
	s_waitcnt lgkmcnt(0)
	s_barrier
	s_waitcnt lgkmcnt(0)
	v_mfma_f32_16x16x32_bf16 v[148:151], v[64:67], v[180:183], v[148:151]
	v_mfma_f32_16x16x32_bf16 v[144:147], v[72:75], v[180:183], v[144:147]
	v_mfma_f32_16x16x32_bf16 v[132:135], v[64:67], v[188:191], v[132:135]
	v_mfma_f32_16x16x32_bf16 v[128:131], v[72:75], v[188:191], v[128:131]
	v_mfma_f32_16x16x32_bf16 v[116:119], v[64:67], v[196:199], v[116:119]
	v_mfma_f32_16x16x32_bf16 v[112:115], v[72:75], v[196:199], v[112:115]
	v_mfma_f32_16x16x32_bf16 v[104:107], v[64:67], v[212:215], v[104:107]
	v_mfma_f32_16x16x32_bf16 v[100:103], v[72:75], v[212:215], v[100:103]
	v_mfma_f32_16x16x32_bf16 v[148:151], v[68:71], v[184:187], v[148:151]
	v_mfma_f32_16x16x32_bf16 v[144:147], v[76:79], v[184:187], v[144:147]
	v_mfma_f32_16x16x32_bf16 v[132:135], v[68:71], v[192:195], v[132:135]
	v_mfma_f32_16x16x32_bf16 v[128:131], v[76:79], v[192:195], v[128:131]
	v_mfma_f32_16x16x32_bf16 v[116:119], v[68:71], v[208:211], v[116:119]
	v_mfma_f32_16x16x32_bf16 v[112:115], v[76:79], v[208:211], v[112:115]
	v_mfma_f32_16x16x32_bf16 v[104:107], v[68:71], v[216:219], v[104:107]
	v_mfma_f32_16x16x32_bf16 v[100:103], v[76:79], v[216:219], v[100:103]
	v_mfma_f32_16x16x32_bf16 v[152:155], v[80:83], v[180:183], v[152:155]
	v_mfma_f32_16x16x32_bf16 v[156:159], v[88:91], v[180:183], v[156:159]
	v_mfma_f32_16x16x32_bf16 v[136:139], v[80:83], v[188:191], v[136:139]
	v_mfma_f32_16x16x32_bf16 v[140:143], v[88:91], v[188:191], v[140:143]
	v_mfma_f32_16x16x32_bf16 v[120:123], v[80:83], v[196:199], v[120:123]
	v_mfma_f32_16x16x32_bf16 v[124:127], v[88:91], v[196:199], v[124:127]
	v_mfma_f32_16x16x32_bf16 v[96:99], v[80:83], v[212:215], v[96:99]
	v_mfma_f32_16x16x32_bf16 v[108:111], v[88:91], v[212:215], v[108:111]
	v_mfma_f32_16x16x32_bf16 v[152:155], v[84:87], v[184:187], v[152:155]
	v_mfma_f32_16x16x32_bf16 v[156:159], v[92:95], v[184:187], v[156:159]
	v_mfma_f32_16x16x32_bf16 v[136:139], v[84:87], v[192:195], v[136:139]
	v_mfma_f32_16x16x32_bf16 v[140:143], v[92:95], v[192:195], v[140:143]
	v_mfma_f32_16x16x32_bf16 v[120:123], v[84:87], v[208:211], v[120:123]
	v_mfma_f32_16x16x32_bf16 v[124:127], v[92:95], v[208:211], v[124:127]
	v_mfma_f32_16x16x32_bf16 v[96:99], v[84:87], v[216:219], v[96:99]
	v_mfma_f32_16x16x32_bf16 v[108:111], v[92:95], v[216:219], v[108:111]
	s_barrier
	s_add_i32 s64, s89, s70
	v_lshl_add_u64 v[220:221], v[220:221], 0, s[36:37]
	s_mov_b32 m0, s64
	ds_read_b128 v[180:183], v205 offset:49152
	ds_read_b128 v[184:187], v205 offset:50176
	ds_read_b128 v[188:191], v205 offset:51200
	ds_read_b128 v[192:195], v205 offset:52224
	ds_read_b128 v[196:199], v205 offset:53248
	ds_read_b128 v[208:211], v205 offset:54272
	ds_read_b128 v[212:215], v205 offset:55296
	ds_read_b128 v[216:219], v205 offset:56320
	global_load_lds_dwordx4 v[220:221], off
	s_add_i32 m0, s64, 0x2000
	s_add_u32 s62, s62, 0x40080
	v_lshl_add_u64 v[220:221], v[222:223], 0, s[36:37]
	s_addc_u32 s63, s63, 0
	s_add_i32 s64, s90, s70
	global_load_lds_dwordx4 v[220:221], off
	v_lshl_add_u64 v[220:221], s[62:63], 0, v[164:165]
	s_mov_b32 m0, s64
	s_nop 0
	global_load_lds_dwordx4 v[220:221], off
	v_lshl_add_u64 v[220:221], s[62:63], 0, v[160:161]
	s_add_i32 m0, s64, 0x2000
	s_nop 0
	global_load_lds_dwordx4 v[220:221], off
	v_lshl_add_u64 v[220:221], v[224:225], 0, s[36:37]
	s_mov_b32 m0, s76
	s_nop 0
	global_load_lds_dwordx4 v[220:221], off
	v_lshl_add_u64 v[220:221], v[226:227], 0, s[36:37]
	s_mov_b32 m0, s77
	s_nop 0
	global_load_lds_dwordx4 v[220:221], off
	s_waitcnt vmcnt(8)
	s_waitcnt lgkmcnt(0)
	s_barrier
	s_waitcnt lgkmcnt(0)
	v_mfma_f32_16x16x32_bf16 v[52:55], v[64:67], v[180:183], v[52:55]
	v_mfma_f32_16x16x32_bf16 v[48:51], v[72:75], v[180:183], v[48:51]
	v_mfma_f32_16x16x32_bf16 v[36:39], v[64:67], v[188:191], v[36:39]
	v_mfma_f32_16x16x32_bf16 v[32:35], v[72:75], v[188:191], v[32:35]
	v_mfma_f32_16x16x32_bf16 v[20:23], v[64:67], v[196:199], v[20:23]
	v_mfma_f32_16x16x32_bf16 v[16:19], v[72:75], v[196:199], v[16:19]
	v_mfma_f32_16x16x32_bf16 v[8:11], v[64:67], v[212:215], v[8:11]
	v_mfma_f32_16x16x32_bf16 v[4:7], v[72:75], v[212:215], v[4:7]
	v_mfma_f32_16x16x32_bf16 v[52:55], v[68:71], v[184:187], v[52:55]
	v_mfma_f32_16x16x32_bf16 v[48:51], v[76:79], v[184:187], v[48:51]
	v_mfma_f32_16x16x32_bf16 v[36:39], v[68:71], v[192:195], v[36:39]
	v_mfma_f32_16x16x32_bf16 v[32:35], v[76:79], v[192:195], v[32:35]
	v_mfma_f32_16x16x32_bf16 v[20:23], v[68:71], v[208:211], v[20:23]
	v_mfma_f32_16x16x32_bf16 v[16:19], v[76:79], v[208:211], v[16:19]
	v_mfma_f32_16x16x32_bf16 v[8:11], v[68:71], v[216:219], v[8:11]
	v_mfma_f32_16x16x32_bf16 v[4:7], v[76:79], v[216:219], v[4:7]
	v_mfma_f32_16x16x32_bf16 v[56:59], v[80:83], v[180:183], v[56:59]
	v_mfma_f32_16x16x32_bf16 v[60:63], v[88:91], v[180:183], v[60:63]
	v_mfma_f32_16x16x32_bf16 v[40:43], v[80:83], v[188:191], v[40:43]
	v_mfma_f32_16x16x32_bf16 v[44:47], v[88:91], v[188:191], v[44:47]
	v_mfma_f32_16x16x32_bf16 v[24:27], v[80:83], v[196:199], v[24:27]
	v_mfma_f32_16x16x32_bf16 v[28:31], v[88:91], v[196:199], v[28:31]
	v_mfma_f32_16x16x32_bf16 v[0:3], v[80:83], v[212:215], v[0:3]
	v_mfma_f32_16x16x32_bf16 v[12:15], v[88:91], v[212:215], v[12:15]
	v_mfma_f32_16x16x32_bf16 v[56:59], v[84:87], v[184:187], v[56:59]
	v_mfma_f32_16x16x32_bf16 v[60:63], v[92:95], v[184:187], v[60:63]
	v_mfma_f32_16x16x32_bf16 v[40:43], v[84:87], v[192:195], v[40:43]
	v_mfma_f32_16x16x32_bf16 v[44:47], v[92:95], v[192:195], v[44:47]
	v_mfma_f32_16x16x32_bf16 v[24:27], v[84:87], v[208:211], v[24:27]
	v_mfma_f32_16x16x32_bf16 v[28:31], v[92:95], v[208:211], v[28:31]
	v_mfma_f32_16x16x32_bf16 v[0:3], v[84:87], v[216:219], v[0:3]
	v_mfma_f32_16x16x32_bf16 v[12:15], v[92:95], v[216:219], v[12:15]
	s_add_i32 s88, s88, 2
	s_add_u32 s60, s60, 0x100
	s_addc_u32 s61, s61, 0
	s_add_u32 s86, s86, 0x100
	s_addc_u32 s87, s87, 0
	s_cmp_gt_u32 s88, 13
	s_barrier
	s_cbranch_scc0 .LBB0_1552
	s_setprio 0
	s_and_b64 vcc, exec, s[38:39]
	s_cbranch_vccz .LBB0_1555
	s_barrier

.Lgp_1704:
.LBB0_1704:
	ds_read_b128 v[140:143], v149
	ds_read_b128 v[152:155], v149 offset:1024
	ds_read_b128 v[156:159], v149 offset:2048
	ds_read_b128 v[160:163], v149 offset:3072
	ds_read_b128 v[164:167], v150
	ds_read_b128 v[168:171], v150 offset:1024
	ds_read_b128 v[172:175], v150 offset:2048
	ds_read_b128 v[176:179], v150 offset:3072
	s_add_u32 s46, s44, 0xfff50080
	s_addc_u32 s47, s45, -1
	s_cmp_eq_u32 s68, 40
	s_cselect_b32 s49, s5, s47
	s_cselect_b32 s48, s4, s46
	s_cselect_b32 s47, s39, s67
	s_cselect_b32 s46, s38, s66
	v_lshl_add_u64 v[144:145], s[44:45], 0, v[132:133]
	s_add_i32 m0, s53, 0xc000
	ds_read_b128 v[180:183], v151
	ds_read_b128 v[184:187], v151 offset:1024
	ds_read_b128 v[188:191], v151 offset:2048
	ds_read_b128 v[192:195], v151 offset:3072
	ds_read_b128 v[196:199], v151 offset:4096
	ds_read_b128 v[202:205], v151 offset:5120
	ds_read_b128 v[206:209], v151 offset:6144
	ds_read_b128 v[210:213], v151 offset:7168
	global_load_lds_dwordx4 v[144:145], off
	v_lshl_add_u64 v[144:145], s[44:45], 0, v[134:135]
	s_add_i32 m0, s53, 0xe000
	s_nop 0
	global_load_lds_dwordx4 v[144:145], off
	s_waitcnt vmcnt(8)
	s_waitcnt lgkmcnt(0)
	s_barrier
	s_waitcnt lgkmcnt(0)
	v_mfma_f32_16x16x32_bf16 v[124:127], v[140:143], v[180:183], v[124:127]
	v_mfma_f32_16x16x32_bf16 v[120:123], v[156:159], v[180:183], v[120:123]
	v_mfma_f32_16x16x32_bf16 v[112:115], v[140:143], v[188:191], v[112:115]
	v_mfma_f32_16x16x32_bf16 v[104:107], v[156:159], v[188:191], v[104:107]
	v_mfma_f32_16x16x32_bf16 v[96:99], v[140:143], v[196:199], v[96:99]
	v_mfma_f32_16x16x32_bf16 v[88:91], v[156:159], v[196:199], v[88:91]
	v_mfma_f32_16x16x32_bf16 v[80:83], v[140:143], v[206:209], v[80:83]
	v_mfma_f32_16x16x32_bf16 v[72:75], v[156:159], v[206:209], v[72:75]
	v_mfma_f32_16x16x32_bf16 v[124:127], v[152:155], v[184:187], v[124:127]
	v_mfma_f32_16x16x32_bf16 v[120:123], v[160:163], v[184:187], v[120:123]
	v_mfma_f32_16x16x32_bf16 v[112:115], v[152:155], v[192:195], v[112:115]
	v_mfma_f32_16x16x32_bf16 v[104:107], v[160:163], v[192:195], v[104:107]
	v_mfma_f32_16x16x32_bf16 v[96:99], v[152:155], v[202:205], v[96:99]
	v_mfma_f32_16x16x32_bf16 v[88:91], v[160:163], v[202:205], v[88:91]
	v_mfma_f32_16x16x32_bf16 v[80:83], v[152:155], v[210:213], v[80:83]
	v_mfma_f32_16x16x32_bf16 v[72:75], v[160:163], v[210:213], v[72:75]
	v_mfma_f32_16x16x32_bf16 v[116:119], v[164:167], v[180:183], v[116:119]
	v_mfma_f32_16x16x32_bf16 v[108:111], v[172:175], v[180:183], v[108:111]
	v_mfma_f32_16x16x32_bf16 v[100:103], v[164:167], v[188:191], v[100:103]
	v_mfma_f32_16x16x32_bf16 v[92:95], v[172:175], v[188:191], v[92:95]
	v_mfma_f32_16x16x32_bf16 v[84:87], v[164:167], v[196:199], v[84:87]
	v_mfma_f32_16x16x32_bf16 v[76:79], v[172:175], v[196:199], v[76:79]
	v_mfma_f32_16x16x32_bf16 v[68:71], v[164:167], v[206:209], v[68:71]
	v_mfma_f32_16x16x32_bf16 v[64:67], v[172:175], v[206:209], v[64:67]
	v_mfma_f32_16x16x32_bf16 v[116:119], v[168:171], v[184:187], v[116:119]
	v_mfma_f32_16x16x32_bf16 v[108:111], v[176:179], v[184:187], v[108:111]
	v_mfma_f32_16x16x32_bf16 v[100:103], v[168:171], v[192:195], v[100:103]
	v_mfma_f32_16x16x32_bf16 v[92:95], v[176:179], v[192:195], v[92:95]
	v_mfma_f32_16x16x32_bf16 v[84:87], v[168:171], v[202:205], v[84:87]
	v_mfma_f32_16x16x32_bf16 v[76:79], v[176:179], v[202:205], v[76:79]
	v_mfma_f32_16x16x32_bf16 v[68:71], v[168:171], v[210:213], v[68:71]
	v_mfma_f32_16x16x32_bf16 v[64:67], v[176:179], v[210:213], v[64:67]
	s_barrier
	s_add_i32 s69, s62, s52
	v_lshl_add_u64 v[144:145], s[46:47], 0, v[130:131]
	s_mov_b32 m0, s69
	ds_read_b128 v[180:183], v151 offset:16384
	ds_read_b128 v[184:187], v151 offset:17408
	ds_read_b128 v[188:191], v151 offset:18432
	ds_read_b128 v[192:195], v151 offset:19456
	ds_read_b128 v[196:199], v151 offset:20480
	ds_read_b128 v[202:205], v151 offset:21504
	ds_read_b128 v[206:209], v151 offset:22528
	ds_read_b128 v[210:213], v151 offset:23552
	global_load_lds_dwordx4 v[144:145], off
	s_add_i32 m0, s69, 0x2000
	s_add_u32 s70, s46, 0xb0000
	v_lshl_add_u64 v[214:215], s[46:47], 0, v[128:129]
	s_addc_u32 s71, s47, 0
	s_add_i32 s69, s63, s52
	global_load_lds_dwordx4 v[214:215], off
	v_lshl_add_u64 v[216:217], s[70:71], 0, v[130:131]
	s_mov_b32 m0, s69
	v_lshl_add_u64 v[218:219], s[48:49], 0, v[128:129]
	global_load_lds_dwordx4 v[216:217], off
	v_lshl_add_u64 v[216:217], s[70:71], 0, v[128:129]
	s_add_i32 m0, s69, 0x2000
	s_nop 0
	global_load_lds_dwordx4 v[216:217], off
	v_lshl_add_u64 v[216:217], s[48:49], 0, v[130:131]
	s_mov_b32 m0, s53
	s_nop 0
	global_load_lds_dwordx4 v[216:217], off
	s_mov_b32 m0, s54
	s_nop 0
	global_load_lds_dwordx4 v[218:219], off
	s_waitcnt vmcnt(8)
	s_waitcnt lgkmcnt(0)
	s_barrier
	s_waitcnt lgkmcnt(0)
	v_mfma_f32_16x16x32_bf16 v[60:63], v[140:143], v[180:183], v[60:63]
	v_mfma_f32_16x16x32_bf16 v[56:59], v[156:159], v[180:183], v[56:59]
	v_mfma_f32_16x16x32_bf16 v[48:51], v[140:143], v[188:191], v[48:51]
	v_mfma_f32_16x16x32_bf16 v[40:43], v[156:159], v[188:191], v[40:43]
	v_mfma_f32_16x16x32_bf16 v[32:35], v[140:143], v[196:199], v[32:35]
	v_mfma_f32_16x16x32_bf16 v[24:27], v[156:159], v[196:199], v[24:27]
	v_mfma_f32_16x16x32_bf16 v[16:19], v[140:143], v[206:209], v[16:19]
	v_mfma_f32_16x16x32_bf16 v[8:11], v[156:159], v[206:209], v[8:11]
	v_mfma_f32_16x16x32_bf16 v[60:63], v[152:155], v[184:187], v[60:63]
	v_mfma_f32_16x16x32_bf16 v[56:59], v[160:163], v[184:187], v[56:59]
	v_mfma_f32_16x16x32_bf16 v[48:51], v[152:155], v[192:195], v[48:51]
	v_mfma_f32_16x16x32_bf16 v[40:43], v[160:163], v[192:195], v[40:43]
	v_mfma_f32_16x16x32_bf16 v[32:35], v[152:155], v[202:205], v[32:35]
	v_mfma_f32_16x16x32_bf16 v[24:27], v[160:163], v[202:205], v[24:27]
	v_mfma_f32_16x16x32_bf16 v[16:19], v[152:155], v[210:213], v[16:19]
	v_mfma_f32_16x16x32_bf16 v[8:11], v[160:163], v[210:213], v[8:11]
	v_mfma_f32_16x16x32_bf16 v[52:55], v[164:167], v[180:183], v[52:55]
	v_mfma_f32_16x16x32_bf16 v[44:47], v[172:175], v[180:183], v[44:47]
	v_mfma_f32_16x16x32_bf16 v[36:39], v[164:167], v[188:191], v[36:39]
	v_mfma_f32_16x16x32_bf16 v[28:31], v[172:175], v[188:191], v[28:31]
	v_mfma_f32_16x16x32_bf16 v[20:23], v[164:167], v[196:199], v[20:23]
	v_mfma_f32_16x16x32_bf16 v[12:15], v[172:175], v[196:199], v[12:15]
	v_mfma_f32_16x16x32_bf16 v[4:7], v[164:167], v[206:209], v[4:7]
	v_mfma_f32_16x16x32_bf16 v[0:3], v[172:175], v[206:209], v[0:3]
	v_mfma_f32_16x16x32_bf16 v[52:55], v[168:171], v[184:187], v[52:55]
	v_mfma_f32_16x16x32_bf16 v[44:47], v[176:179], v[184:187], v[44:47]
	v_mfma_f32_16x16x32_bf16 v[36:39], v[168:171], v[192:195], v[36:39]
	v_mfma_f32_16x16x32_bf16 v[28:31], v[176:179], v[192:195], v[28:31]
	v_mfma_f32_16x16x32_bf16 v[20:23], v[168:171], v[202:205], v[20:23]
	v_mfma_f32_16x16x32_bf16 v[12:15], v[176:179], v[202:205], v[12:15]
	v_mfma_f32_16x16x32_bf16 v[4:7], v[168:171], v[210:213], v[4:7]
	v_mfma_f32_16x16x32_bf16 v[0:3], v[176:179], v[210:213], v[0:3]
	s_barrier
	s_add_i32 s69, 0, 0x18000
	s_add_i32 s70, 0, 0x1c000
	v_add_u32_e32 v160, s69, v147
	v_add_u32_e32 v176, s70, v147
	ds_read_b128 v[140:143], v160
	ds_read_b128 v[152:155], v160 offset:1024
	ds_read_b128 v[156:159], v160 offset:2048
	ds_read_b128 v[160:163], v160 offset:3072
	ds_read_b128 v[164:167], v176
	ds_read_b128 v[168:171], v176 offset:1024
	ds_read_b128 v[172:175], v176 offset:2048
	ds_read_b128 v[176:179], v176 offset:3072
	s_add_u32 s48, s48, 0xb0000
	s_addc_u32 s49, s49, 0
	s_mov_b32 m0, s55
	v_lshl_add_u64 v[220:221], s[48:49], 0, v[130:131]
	ds_read_b128 v[180:183], v151 offset:32768
	ds_read_b128 v[184:187], v151 offset:33792
	ds_read_b128 v[188:191], v151 offset:34816
	ds_read_b128 v[192:195], v151 offset:35840
	ds_read_b128 v[196:199], v151 offset:36864
	ds_read_b128 v[202:205], v151 offset:37888
	ds_read_b128 v[206:209], v151 offset:38912
	ds_read_b128 v[210:213], v151 offset:39936
	global_load_lds_dwordx4 v[220:221], off
	v_lshl_add_u64 v[220:221], s[48:49], 0, v[128:129]
	s_mov_b32 m0, s56
	s_nop 0
	global_load_lds_dwordx4 v[220:221], off
	s_waitcnt vmcnt(8)
	s_waitcnt lgkmcnt(0)
	s_barrier
	s_waitcnt lgkmcnt(0)
	v_mfma_f32_16x16x32_bf16 v[124:127], v[140:143], v[180:183], v[124:127]
	v_mfma_f32_16x16x32_bf16 v[120:123], v[156:159], v[180:183], v[120:123]
	v_mfma_f32_16x16x32_bf16 v[112:115], v[140:143], v[188:191], v[112:115]
	v_mfma_f32_16x16x32_bf16 v[104:107], v[156:159], v[188:191], v[104:107]
	v_mfma_f32_16x16x32_bf16 v[96:99], v[140:143], v[196:199], v[96:99]
	v_mfma_f32_16x16x32_bf16 v[88:91], v[156:159], v[196:199], v[88:91]
	v_mfma_f32_16x16x32_bf16 v[80:83], v[140:143], v[206:209], v[80:83]
	v_mfma_f32_16x16x32_bf16 v[72:75], v[156:159], v[206:209], v[72:75]
	v_mfma_f32_16x16x32_bf16 v[124:127], v[152:155], v[184:187], v[124:127]
	v_mfma_f32_16x16x32_bf16 v[120:123], v[160:163], v[184:187], v[120:123]
	v_mfma_f32_16x16x32_bf16 v[112:115], v[152:155], v[192:195], v[112:115]
	v_mfma_f32_16x16x32_bf16 v[104:107], v[160:163], v[192:195], v[104:107]
	v_mfma_f32_16x16x32_bf16 v[96:99], v[152:155], v[202:205], v[96:99]
	v_mfma_f32_16x16x32_bf16 v[88:91], v[160:163], v[202:205], v[88:91]
	v_mfma_f32_16x16x32_bf16 v[80:83], v[152:155], v[210:213], v[80:83]
	v_mfma_f32_16x16x32_bf16 v[72:75], v[160:163], v[210:213], v[72:75]
	v_mfma_f32_16x16x32_bf16 v[116:119], v[164:167], v[180:183], v[116:119]
	v_mfma_f32_16x16x32_bf16 v[108:111], v[172:175], v[180:183], v[108:111]
	v_mfma_f32_16x16x32_bf16 v[100:103], v[164:167], v[188:191], v[100:103]
	v_mfma_f32_16x16x32_bf16 v[92:95], v[172:175], v[188:191], v[92:95]
	v_mfma_f32_16x16x32_bf16 v[84:87], v[164:167], v[196:199], v[84:87]
	v_mfma_f32_16x16x32_bf16 v[76:79], v[172:175], v[196:199], v[76:79]
	v_mfma_f32_16x16x32_bf16 v[68:71], v[164:167], v[206:209], v[68:71]
	v_mfma_f32_16x16x32_bf16 v[64:67], v[172:175], v[206:209], v[64:67]
	v_mfma_f32_16x16x32_bf16 v[116:119], v[168:171], v[184:187], v[116:119]
	v_mfma_f32_16x16x32_bf16 v[108:111], v[176:179], v[184:187], v[108:111]
	v_mfma_f32_16x16x32_bf16 v[100:103], v[168:171], v[192:195], v[100:103]
	v_mfma_f32_16x16x32_bf16 v[92:95], v[176:179], v[192:195], v[92:95]
	v_mfma_f32_16x16x32_bf16 v[84:87], v[168:171], v[202:205], v[84:87]
	v_mfma_f32_16x16x32_bf16 v[76:79], v[176:179], v[202:205], v[76:79]
	v_mfma_f32_16x16x32_bf16 v[68:71], v[168:171], v[210:213], v[68:71]
	v_mfma_f32_16x16x32_bf16 v[64:67], v[176:179], v[210:213], v[64:67]
	s_barrier
	s_add_i32 s48, s69, s52
	v_lshl_add_u64 v[144:145], v[144:145], 0, s[10:11]
	s_mov_b32 m0, s48
	ds_read_b128 v[180:183], v151 offset:49152
	ds_read_b128 v[184:187], v151 offset:50176
	ds_read_b128 v[188:191], v151 offset:51200
	ds_read_b128 v[192:195], v151 offset:52224
	ds_read_b128 v[196:199], v151 offset:53248
	ds_read_b128 v[202:205], v151 offset:54272
	ds_read_b128 v[206:209], v151 offset:55296
	ds_read_b128 v[210:213], v151 offset:56320
	global_load_lds_dwordx4 v[144:145], off
	s_add_i32 m0, s48, 0x2000
	s_add_u32 s46, s46, 0xb0080
	v_lshl_add_u64 v[144:145], v[214:215], 0, s[10:11]
	s_addc_u32 s47, s47, 0
	s_add_i32 s48, s70, s52
	global_load_lds_dwordx4 v[144:145], off
	v_lshl_add_u64 v[144:145], s[46:47], 0, v[130:131]
	s_mov_b32 m0, s48
	s_nop 0
	global_load_lds_dwordx4 v[144:145], off
	v_lshl_add_u64 v[144:145], s[46:47], 0, v[128:129]
	s_add_i32 m0, s48, 0x2000
	s_nop 0
	global_load_lds_dwordx4 v[144:145], off
	v_lshl_add_u64 v[144:145], v[216:217], 0, s[10:11]
	s_mov_b32 m0, s58
	s_nop 0
	global_load_lds_dwordx4 v[144:145], off
	v_lshl_add_u64 v[144:145], v[218:219], 0, s[10:11]
	s_mov_b32 m0, s59
	s_nop 0
	global_load_lds_dwordx4 v[144:145], off
	s_waitcnt vmcnt(8)
	s_waitcnt lgkmcnt(0)
	s_barrier
	s_waitcnt lgkmcnt(0)
	v_mfma_f32_16x16x32_bf16 v[60:63], v[140:143], v[180:183], v[60:63]
	v_mfma_f32_16x16x32_bf16 v[56:59], v[156:159], v[180:183], v[56:59]
	v_mfma_f32_16x16x32_bf16 v[48:51], v[140:143], v[188:191], v[48:51]
	v_mfma_f32_16x16x32_bf16 v[40:43], v[156:159], v[188:191], v[40:43]
	v_mfma_f32_16x16x32_bf16 v[32:35], v[140:143], v[196:199], v[32:35]
	v_mfma_f32_16x16x32_bf16 v[24:27], v[156:159], v[196:199], v[24:27]
	v_mfma_f32_16x16x32_bf16 v[16:19], v[140:143], v[206:209], v[16:19]
	v_mfma_f32_16x16x32_bf16 v[8:11], v[156:159], v[206:209], v[8:11]
	v_mfma_f32_16x16x32_bf16 v[60:63], v[152:155], v[184:187], v[60:63]
	v_mfma_f32_16x16x32_bf16 v[56:59], v[160:163], v[184:187], v[56:59]
	v_mfma_f32_16x16x32_bf16 v[48:51], v[152:155], v[192:195], v[48:51]
	v_mfma_f32_16x16x32_bf16 v[40:43], v[160:163], v[192:195], v[40:43]
	v_mfma_f32_16x16x32_bf16 v[32:35], v[152:155], v[202:205], v[32:35]
	v_mfma_f32_16x16x32_bf16 v[24:27], v[160:163], v[202:205], v[24:27]
	v_mfma_f32_16x16x32_bf16 v[16:19], v[152:155], v[210:213], v[16:19]
	v_mfma_f32_16x16x32_bf16 v[8:11], v[160:163], v[210:213], v[8:11]
	v_mfma_f32_16x16x32_bf16 v[52:55], v[164:167], v[180:183], v[52:55]
	v_mfma_f32_16x16x32_bf16 v[44:47], v[172:175], v[180:183], v[44:47]
	v_mfma_f32_16x16x32_bf16 v[36:39], v[164:167], v[188:191], v[36:39]
	v_mfma_f32_16x16x32_bf16 v[28:31], v[172:175], v[188:191], v[28:31]
	v_mfma_f32_16x16x32_bf16 v[20:23], v[164:167], v[196:199], v[20:23]
	v_mfma_f32_16x16x32_bf16 v[12:15], v[172:175], v[196:199], v[12:15]
	v_mfma_f32_16x16x32_bf16 v[4:7], v[164:167], v[206:209], v[4:7]
	v_mfma_f32_16x16x32_bf16 v[0:3], v[172:175], v[206:209], v[0:3]
	v_mfma_f32_16x16x32_bf16 v[52:55], v[168:171], v[184:187], v[52:55]
	v_mfma_f32_16x16x32_bf16 v[44:47], v[176:179], v[184:187], v[44:47]
	v_mfma_f32_16x16x32_bf16 v[36:39], v[168:171], v[192:195], v[36:39]
	v_mfma_f32_16x16x32_bf16 v[28:31], v[176:179], v[192:195], v[28:31]
	v_mfma_f32_16x16x32_bf16 v[20:23], v[168:171], v[202:205], v[20:23]
	v_mfma_f32_16x16x32_bf16 v[12:15], v[176:179], v[202:205], v[12:15]
	v_mfma_f32_16x16x32_bf16 v[4:7], v[168:171], v[210:213], v[4:7]
	v_mfma_f32_16x16x32_bf16 v[0:3], v[176:179], v[210:213], v[0:3]
	s_add_i32 s68, s68, 2
	s_add_u32 s44, s44, 0x100
	s_addc_u32 s45, s45, 0
	s_add_u32 s66, s66, 0x100
	s_addc_u32 s67, s67, 0
	s_cmp_gt_u32 s68, 41
	s_barrier
	s_cbranch_scc0 .LBB0_1704
	s_setprio 0
	s_and_b64 vcc, exec, s[12:13]
	s_cbranch_vccz .LBB0_1707
	s_barrier
